# page loop K/V loads with system-scope non-temporal policy (sc0 sc1 nt) instead of nt
# speedup vs baseline: 1.0090x; 1.0076x over previous
.LBB0_322:
	v_mov_b32_e32 v120, v158
	s_load_dwordx2 s[4:5], s[42:43], 0x40
	s_load_dwordx2 s[2:3], s[42:43], 0x100
	s_ashr_i32 s41, s40, 31
	s_ashr_i32 s1, s40, 6
	s_lshl_b64 s[6:7], s[40:41], 2
	s_waitcnt lgkmcnt(0)
	s_add_u32 s4, s4, s6
	s_addc_u32 s5, s5, s7
	global_load_dword v4, v1, s[4:5]
	s_load_dwordx4 s[4:7], s[42:43], 0x10
	s_load_dwordx2 s[8:9], s[42:43], 0x20
	s_mul_i32 s11, s74, 0xa00
	s_mul_i32 s10, s1, 0x5800
	v_ashrrev_i32_e32 v160, 4, v120
	v_lshlrev_b32_e32 v2, 6, v160
	v_ashrrev_i32_e32 v3, 31, v2
	v_lshlrev_b64 v[2:3], 1, v[2:3]
	v_and_b32_e32 v159, 15, v120
	v_lshlrev_b32_e32 v0, 3, v159
	v_ashrrev_i32_e32 v121, 31, v120
	s_mov_b32 s38, s14
	s_mov_b32 s39, s14
	v_lshlrev_b32_e32 v161, 4, v120
	s_mov_b32 s22, 0x1e400
	s_mov_b32 s28, 0x1d000
	s_mov_b32 s29, 0x1d400
	s_mov_b32 s35, 0x1d800
	s_mov_b32 s41, 0x1dc00
	v_lshlrev_b32_e32 v162, 2, v160
	v_mov_b32_e32 v118, 0
	s_mov_b32 s15, s14
	s_mov_b32 s19, s14
	v_mov_b32_e32 v151, 0xf149f2ca
	v_mov_b32_e32 v124, v118
	v_mov_b32_e32 v125, v118
	v_mov_b32_e32 v128, v118
	v_mov_b32_e32 v129, v118
	v_mov_b32_e32 v126, v118
	v_mov_b32_e32 v127, v118
	v_mov_b32_e32 v132, v118
	v_mov_b32_e32 v133, v118
	v_mov_b32_e32 v130, v118
	v_mov_b32_e32 v131, v118
	v_mov_b32_e32 v150, 0xf149f2ca
	v_mov_b32_e32 v144, 0xf149f2ca
	v_mov_b32_e32 v142, 0xf149f2ca
	s_waitcnt vmcnt(0)
	v_readfirstlane_b32 s0, v4
	s_add_i32 s16, s0, s11
	s_ashr_i32 s17, s16, 31
	s_lshl_b64 s[24:25], s[16:17], 17
	s_waitcnt lgkmcnt(0)
	s_add_u32 s12, s4, s24
	s_addc_u32 s0, s5, s25
	s_and_b32 s13, s0, 0xffff
	s_add_u32 s4, s6, s24
	s_addc_u32 s0, s7, s25
	s_lshl_b64 s[6:7], s[16:17], 11
	s_and_b32 s5, s0, 0xffff
	s_add_u32 s16, s8, s6
	s_addc_u32 s6, s9, s7
	s_lshl_b32 s8, s1, 2
	s_and_b32 s0, s40, 63
	s_add_i32 s7, s10, 0x5800000
	s_and_b32 s17, s6, 0xffff
	s_add_i32 s6, s8, 0x4000
	s_mul_hi_i32 s9, s6, 0x1600
	s_add_u32 s6, s2, s7
	s_addc_u32 s7, s3, s9
	s_add_i32 s9, s8, 0x4001
	s_add_i32 s11, s10, 0x5801600
	v_lshl_add_u64 v[4:5], s[6:7], 0, v[2:3]
	s_mul_hi_i32 s7, s9, 0x1600
	s_add_u32 s6, s2, s11
	s_addc_u32 s7, s3, s7
	s_add_i32 s9, s8, 0x4002
	s_add_i32 s10, s10, 0x5802c00
	v_lshl_add_u64 v[4:5], v[4:5], 0, v[0:1]
	s_mov_b32 s11, 0xb600000
	v_lshl_add_u64 v[6:7], s[6:7], 0, v[2:3]
	s_mul_hi_i32 s7, s9, 0x1600
	s_add_u32 s6, s2, s10
	v_add_co_u32_e32 v4, vcc, s11, v4
	s_addc_u32 s7, s3, s7
	s_addk_i32 s8, 0x4003
	v_addc_co_u32_e32 v5, vcc, 0, v5, vcc
	v_lshl_add_u64 v[6:7], v[6:7], 0, v[0:1]
	v_lshl_add_u64 v[8:9], s[6:7], 0, v[2:3]
	s_mul_hi_i32 s7, s8, 0x1600
	s_mulk_i32 s8, 0x1600
	v_add_co_u32_e32 v6, vcc, s11, v6
	s_add_u32 s6, s2, s8
	s_nop 0
	v_addc_co_u32_e32 v7, vcc, 0, v7, vcc
	v_lshl_add_u64 v[8:9], v[8:9], 0, v[0:1]
	s_addc_u32 s7, s3, s7
	s_add_i32 s8, s1, s20
	v_add_co_u32_e32 v8, vcc, s11, v8
	v_lshl_add_u64 v[2:3], s[6:7], 0, v[2:3]
	s_ashr_i32 s9, s8, 31
	v_addc_co_u32_e32 v9, vcc, 0, v9, vcc
	v_lshl_add_u64 v[2:3], v[2:3], 0, v[0:1]
	s_lshl_b64 s[6:7], s[8:9], 10
	v_add_co_u32_e32 v2, vcc, s11, v2
	s_add_u32 s2, s2, s6
	s_nop 0
	v_addc_co_u32_e32 v3, vcc, 0, v3, vcc
	s_addc_u32 s3, s3, s7
	global_load_dwordx2 v[106:107], v[4:5], off offset:2560
	global_load_dwordx2 v[104:105], v[6:7], off offset:2560
	global_load_dwordx2 v[102:103], v[8:9], off offset:2560
	global_load_dwordx2 v[122:123], v[2:3], off offset:2560
	v_lshl_add_u64 v[2:3], v[120:121], 4, s[2:3]
	s_mov_b32 s1, 0x3080000
	v_add_co_u32_e32 v2, vcc, s1, v2
	s_mov_b32 s36, s12
	s_nop 0
	v_addc_co_u32_e32 v3, vcc, 0, v3, vcc
	global_load_dwordx4 v[98:101], v[2:3], off
	s_mov_b32 s37, s13
	s_mov_b32 s3, 0x1f400
	s_mov_b32 s8, 0x1f800
	s_mov_b32 s2, 0x1f000
	s_mov_b32 s1, 0x1e000
	s_mov_b32 s9, 0x1fc00
	s_mov_b32 s24, 0x1e800
	s_mov_b32 s25, 0x1ec00
	s_mov_b32 s6, s14
	s_mov_b32 s7, s14
	s_mov_b32 s10, s18
	s_mov_b32 s11, s14
	buffer_load_dwordx4 v[50:53], v161, s[36:39], s2 offen sc0 sc1 nt
	buffer_load_dwordx4 v[22:25], v161, s[4:7], s2 offen sc0 sc1 nt
	s_movk_i32 s10, 0x7c0
	buffer_load_dword v167, v162, s[16:19], s10 offen
	buffer_load_dwordx4 v[58:61], v161, s[36:39], s3 offen sc0 sc1 nt
	buffer_load_dwordx4 v[18:21], v161, s[4:7], s3 offen sc0 sc1 nt
	s_movk_i32 s10, 0x7d0
	buffer_load_dword v169, v162, s[16:19], s10 offen
	buffer_load_dwordx4 v[54:57], v161, s[36:39], s8 offen sc0 sc1 nt
	buffer_load_dwordx4 v[26:29], v161, s[4:7], s8 offen sc0 sc1 nt
	s_movk_i32 s10, 0x7e0
	buffer_load_dword v170, v162, s[16:19], s10 offen
	buffer_load_dwordx4 v[62:65], v161, s[36:39], s9 offen sc0 sc1 nt
	buffer_load_dwordx4 v[30:33], v161, s[4:7], s9 offen sc0 sc1 nt
	s_movk_i32 s10, 0x7f0
	buffer_load_dword v171, v162, s[16:19], s10 offen
	buffer_load_dwordx4 v[34:37], v161, s[36:39], s1 offen sc0 sc1 nt
	buffer_load_dwordx4 v[2:5], v161, s[4:7], s1 offen sc0 sc1 nt
	s_movk_i32 s10, 0x780
	buffer_load_dword v168, v162, s[16:19], s10 offen
	buffer_load_dwordx4 v[42:45], v161, s[36:39], s22 offen sc0 sc1 nt
	buffer_load_dwordx4 v[6:9], v161, s[4:7], s22 offen sc0 sc1 nt
	s_movk_i32 s10, 0x790
	buffer_load_dword v164, v162, s[16:19], s10 offen
	buffer_load_dwordx4 v[38:41], v161, s[36:39], s24 offen sc0 sc1 nt
	buffer_load_dwordx4 v[10:13], v161, s[4:7], s24 offen sc0 sc1 nt
	s_movk_i32 s10, 0x7a0
	buffer_load_dword v165, v162, s[16:19], s10 offen
	buffer_load_dwordx4 v[46:49], v161, s[36:39], s25 offen sc0 sc1 nt
	buffer_load_dwordx4 v[14:17], v161, s[4:7], s25 offen sc0 sc1 nt
	s_movk_i32 s10, 0x7b0
	buffer_load_dword v166, v162, s[16:19], s10 offen
	buffer_load_dwordx4 v[82:85], v161, s[36:39], s28 offen sc0 sc1 nt
	buffer_load_dwordx4 v[66:69], v161, s[4:7], s28 offen sc0 sc1 nt
	s_movk_i32 s10, 0x740
	buffer_load_dword v163, v162, s[16:19], s10 offen
	buffer_load_dwordx4 v[86:89], v161, s[36:39], s29 offen sc0 sc1 nt
	buffer_load_dwordx4 v[70:73], v161, s[4:7], s29 offen sc0 sc1 nt
	s_movk_i32 s10, 0x750
	buffer_load_dword v143, v162, s[16:19], s10 offen
	buffer_load_dwordx4 v[90:93], v161, s[36:39], s35 offen sc0 sc1 nt
	buffer_load_dwordx4 v[74:77], v161, s[4:7], s35 offen sc0 sc1 nt
	s_movk_i32 s10, 0x760
	buffer_load_dword v145, v162, s[16:19], s10 offen
	buffer_load_dwordx4 v[94:97], v161, s[36:39], s41 offen sc0 sc1 nt
	buffer_load_dwordx4 v[78:81], v161, s[4:7], s41 offen sc0 sc1 nt
	s_movk_i32 s10, 0x770
	buffer_load_dword v172, v162, s[16:19], s10 offen
	v_cmp_lt_i32_e32 vcc, s0, v120
	v_lshlrev_b32_e32 v0, 2, v159
	s_waitcnt vmcnt(40)
	v_lshlrev_b32_e32 v114, 16, v106
	v_and_b32_e32 v115, 0xffff0000, v106
	v_lshlrev_b32_e32 v116, 16, v107
	v_and_b32_e32 v117, 0xffff0000, v107
	s_waitcnt vmcnt(39)
	v_lshlrev_b32_e32 v110, 16, v104
	v_and_b32_e32 v111, 0xffff0000, v104
	v_lshlrev_b32_e32 v112, 16, v105
	v_and_b32_e32 v113, 0xffff0000, v105
	s_waitcnt vmcnt(38)
	v_lshlrev_b32_e32 v106, 16, v102
	v_and_b32_e32 v107, 0xffff0000, v102
	v_lshlrev_b32_e32 v108, 16, v103
	s_waitcnt vmcnt(36)
	v_cndmask_b32_e32 v99, 0, v99, vcc
	v_cndmask_b32_e32 v98, 0, v98, vcc
	v_cndmask_b32_e32 v100, 0, v100, vcc
	v_add_f32_dpp v99, v99, v99 quad_perm:[1,0,3,2] row_mask:0xf bank_mask:0xf bound_ctrl:1
	v_cndmask_b32_e32 v101, 0, v101, vcc
	v_add_f32_dpp v98, v98, v98 quad_perm:[1,0,3,2] row_mask:0xf bank_mask:0xf bound_ctrl:1
	v_add_f32_dpp v99, v99, v99 quad_perm:[2,3,0,1] row_mask:0xf bank_mask:0xf bound_ctrl:1
	v_add_f32_dpp v100, v100, v100 quad_perm:[1,0,3,2] row_mask:0xf bank_mask:0xf bound_ctrl:1
	v_add_f32_dpp v101, v101, v101 quad_perm:[1,0,3,2] row_mask:0xf bank_mask:0xf bound_ctrl:1
	v_add_f32_dpp v98, v98, v98 quad_perm:[2,3,0,1] row_mask:0xf bank_mask:0xf bound_ctrl:1
	v_add_f32_dpp v99, v99, v99 row_half_mirror row_mask:0xf bank_mask:0xf bound_ctrl:1
	v_add_f32_dpp v100, v100, v100 quad_perm:[2,3,0,1] row_mask:0xf bank_mask:0xf bound_ctrl:1
	v_add_f32_dpp v101, v101, v101 quad_perm:[2,3,0,1] row_mask:0xf bank_mask:0xf bound_ctrl:1
	v_add_f32_dpp v98, v98, v98 row_half_mirror row_mask:0xf bank_mask:0xf bound_ctrl:1
	v_add_f32_dpp v99, v99, v99 row_mirror row_mask:0xf bank_mask:0xf bound_ctrl:1
	v_add_f32_dpp v100, v100, v100 row_half_mirror row_mask:0xf bank_mask:0xf bound_ctrl:1
	v_add_f32_dpp v101, v101, v101 row_half_mirror row_mask:0xf bank_mask:0xf bound_ctrl:1
	v_add_f32_dpp v98, v98, v98 row_mirror row_mask:0xf bank_mask:0xf bound_ctrl:1
	v_readlane_b32 s9, v99, 16
	v_readlane_b32 s22, v99, 48
	v_add_f32_dpp v100, v100, v100 row_mirror row_mask:0xf bank_mask:0xf bound_ctrl:1
	v_add_f32_dpp v119, v101, v101 row_mirror row_mask:0xf bank_mask:0xf bound_ctrl:1
	v_readlane_b32 s0, v98, 0
	v_readlane_b32 s10, v98, 16
	v_readlane_b32 s1, v98, 32
	v_readlane_b32 s11, v98, 48
	v_readlane_b32 s2, v99, 0
	v_readlane_b32 s3, v99, 32
	v_mov_b32_e32 v98, s9
	v_mov_b32_e32 v99, s22
	v_readlane_b32 s24, v100, 16
	v_readlane_b32 s25, v100, 48
	v_pk_add_f32 v[98:99], s[2:3], v[98:99]
	v_readlane_b32 s2, v119, 16
	v_readlane_b32 s3, v119, 48
	v_readlane_b32 s6, v100, 0
	v_readlane_b32 s7, v100, 32
	v_readlane_b32 s8, v119, 0
	v_mov_b32_e32 v100, s24
	v_mov_b32_e32 v101, s25
	v_add_f32_e32 v121, v98, v99
	v_readlane_b32 s9, v119, 32
	v_mov_b32_e32 v98, s2
	v_mov_b32_e32 v99, s3
	v_pk_add_f32 v[100:101], s[6:7], v[100:101]
	v_pk_add_f32 v[98:99], s[8:9], v[98:99]
	v_add_f32_e32 v100, v100, v101
	v_add_f32_e32 v98, v98, v99
	v_cmp_eq_u32_e32 vcc, 2, v160
	v_mov_b32_e32 v99, s11
	v_and_b32_e32 v109, 0xffff0000, v103
	v_cndmask_b32_e32 v98, v98, v100, vcc
	v_cmp_eq_u32_e32 vcc, 1, v160
	v_lshlrev_b32_e32 v102, 16, v122
	v_and_b32_e32 v103, 0xffff0000, v122
	v_cndmask_b32_e32 v100, v98, v121, vcc
	v_mov_b32_e32 v98, s10
	v_pk_add_f32 v[98:99], s[0:1], v[98:99]
	v_cmp_gt_u32_e32 vcc, 16, v120
	v_add_f32_e32 v98, v98, v99
	v_lshlrev_b32_e32 v104, 16, v123
	v_and_b32_e32 v105, 0xffff0000, v123
	v_cndmask_b32_e32 v146, v100, v98, vcc
	s_movk_i32 s2, 0x88
	s_movk_i32 s3, 0x680
	s_mov_b32 s8, 0x1a000
	v_mov_b32_e32 v119, v118
	v_mov_b32_e32 v120, v118
	v_mov_b32_e32 v121, v118
	v_mov_b32_e32 v122, v118
	v_mov_b32_e32 v123, v118
	v_mov_b32_e32 v98, v118
	v_mov_b32_e32 v99, v118
	v_mov_b32_e32 v100, v118
	v_mov_b32_e32 v101, v118
	s_mov_b32 s6, s14
	s_mov_b32 s7, s15
	v_and_b32_e32 v155, 1, v159
	v_and_b32_e32 v156, 2, v159
	v_cmp_ne_u32_e64 s[28:29], 0, v155
	v_cmp_ne_u32_e64 s[24:25], 0, v156
	v_mov_b32_e32 v118, 0
	v_mov_b32_e32 v119, 0
	v_mov_b32_e32 v120, 0
	v_mov_b32_e32 v121, 0
	v_mov_b32_e32 v122, 0
	v_mov_b32_e32 v123, 0
	v_mov_b32_e32 v124, 0
	v_mov_b32_e32 v125, 0
	v_mov_b32_e32 v126, 0
	v_mov_b32_e32 v127, 0
	v_mov_b32_e32 v128, 0
	v_mov_b32_e32 v129, 0
	v_mov_b32_e32 v130, 0
	v_mov_b32_e32 v131, 0
	v_mov_b32_e32 v132, 0
	v_mov_b32_e32 v133, 0
	v_mov_b32_e32 v134, 0xf149f2ca
	v_mov_b32_e32 v135, 0
.Lpg_loop:
	s_waitcnt vmcnt(24)
	v_pk_mul_f32 v[98:99], v[116:117], v[52:53]
	v_pk_mul_f32 v[100:101], v[116:117], v[60:61]
	v_pk_mul_f32 v[174:175], v[116:117], v[56:57]
	v_pk_mul_f32 v[176:177], v[116:117], v[64:65]
	v_pk_fma_f32 v[98:99], v[114:115], v[50:51], v[98:99]
	v_pk_fma_f32 v[100:101], v[114:115], v[58:59], v[100:101]
	v_pk_fma_f32 v[174:175], v[114:115], v[54:55], v[174:175]
	v_pk_fma_f32 v[176:177], v[114:115], v[62:63], v[176:177]
	v_add_f32_e32 v136, v98, v99
	v_add_f32_e32 v137, v100, v101
	v_add_f32_e32 v138, v174, v175
	v_add_f32_e32 v139, v176, v177
	v_pk_mul_f32 v[98:99], v[112:113], v[52:53]
	v_pk_mul_f32 v[100:101], v[112:113], v[60:61]
	v_pk_mul_f32 v[174:175], v[112:113], v[56:57]
	v_pk_mul_f32 v[176:177], v[112:113], v[64:65]
	v_pk_fma_f32 v[98:99], v[110:111], v[50:51], v[98:99]
	v_pk_fma_f32 v[100:101], v[110:111], v[58:59], v[100:101]
	v_pk_fma_f32 v[174:175], v[110:111], v[54:55], v[174:175]
	v_pk_fma_f32 v[176:177], v[110:111], v[62:63], v[176:177]
	v_add_f32_e32 v140, v98, v99
	v_add_f32_e32 v141, v100, v101
	v_add_f32_e32 v142, v174, v175
	v_add_f32_e32 v144, v176, v177
	v_pk_mul_f32 v[98:99], v[108:109], v[52:53]
	v_pk_mul_f32 v[100:101], v[108:109], v[60:61]
	v_pk_mul_f32 v[174:175], v[108:109], v[56:57]
	v_pk_mul_f32 v[176:177], v[108:109], v[64:65]
	v_pk_fma_f32 v[98:99], v[106:107], v[50:51], v[98:99]
	v_pk_fma_f32 v[100:101], v[106:107], v[58:59], v[100:101]
	v_pk_fma_f32 v[174:175], v[106:107], v[54:55], v[174:175]
	v_pk_fma_f32 v[176:177], v[106:107], v[62:63], v[176:177]
	v_add_f32_e32 v147, v98, v99
	v_add_f32_e32 v148, v100, v101
	v_add_f32_e32 v149, v174, v175
	v_add_f32_e32 v150, v176, v177
	v_pk_mul_f32 v[98:99], v[104:105], v[52:53]
	v_pk_mul_f32 v[100:101], v[104:105], v[60:61]
	v_pk_mul_f32 v[174:175], v[104:105], v[56:57]
	v_pk_mul_f32 v[176:177], v[104:105], v[64:65]
	v_pk_fma_f32 v[98:99], v[102:103], v[50:51], v[98:99]
	v_pk_fma_f32 v[100:101], v[102:103], v[58:59], v[100:101]
	v_pk_fma_f32 v[174:175], v[102:103], v[54:55], v[174:175]
	v_pk_fma_f32 v[176:177], v[102:103], v[62:63], v[176:177]
	v_add_f32_e32 v151, v98, v99
	v_add_f32_e32 v152, v100, v101
	v_add_f32_e32 v153, v174, v175
	v_add_f32_e32 v154, v176, v177
	v_add_f32_e32 v155, v146, v171
	v_add_f32_e32 v156, v155, v170
	v_add_f32_e32 v157, v156, v169
	v_add_f32_dpp v136, v136, v136 row_mirror row_mask:0xf bank_mask:0x3 bound_ctrl:1
	v_add_f32_dpp v137, v137, v137 row_mirror row_mask:0xf bank_mask:0x3 bound_ctrl:1
	v_add_f32_dpp v138, v138, v138 row_mirror row_mask:0xf bank_mask:0x3 bound_ctrl:1
	v_add_f32_dpp v139, v139, v139 row_mirror row_mask:0xf bank_mask:0x3 bound_ctrl:1
	v_add_f32_dpp v140, v140, v140 row_mirror row_mask:0xf bank_mask:0x3 bound_ctrl:1
	v_add_f32_dpp v141, v141, v141 row_mirror row_mask:0xf bank_mask:0x3 bound_ctrl:1
	v_add_f32_dpp v142, v142, v142 row_mirror row_mask:0xf bank_mask:0x3 bound_ctrl:1
	v_add_f32_dpp v144, v144, v144 row_mirror row_mask:0xf bank_mask:0x3 bound_ctrl:1
	v_add_f32_dpp v136, v147, v147 row_mirror row_mask:0xf bank_mask:0xc bound_ctrl:1
	v_add_f32_dpp v137, v148, v148 row_mirror row_mask:0xf bank_mask:0xc bound_ctrl:1
	v_add_f32_dpp v138, v149, v149 row_mirror row_mask:0xf bank_mask:0xc bound_ctrl:1
	v_add_f32_dpp v139, v150, v150 row_mirror row_mask:0xf bank_mask:0xc bound_ctrl:1
	v_add_f32_dpp v140, v151, v151 row_mirror row_mask:0xf bank_mask:0xc bound_ctrl:1
	v_add_f32_dpp v141, v152, v152 row_mirror row_mask:0xf bank_mask:0xc bound_ctrl:1
	v_add_f32_dpp v142, v153, v153 row_mirror row_mask:0xf bank_mask:0xc bound_ctrl:1
	v_add_f32_dpp v144, v154, v154 row_mirror row_mask:0xf bank_mask:0xc bound_ctrl:1
	v_add_f32_dpp v136, v136, v136 row_half_mirror row_mask:0xf bank_mask:0x5 bound_ctrl:1
	v_add_f32_dpp v137, v137, v137 row_half_mirror row_mask:0xf bank_mask:0x5 bound_ctrl:1
	v_add_f32_dpp v138, v138, v138 row_half_mirror row_mask:0xf bank_mask:0x5 bound_ctrl:1
	v_add_f32_dpp v139, v139, v139 row_half_mirror row_mask:0xf bank_mask:0x5 bound_ctrl:1
	v_add_f32_dpp v136, v140, v140 row_half_mirror row_mask:0xf bank_mask:0xa bound_ctrl:1
	v_add_f32_dpp v137, v141, v141 row_half_mirror row_mask:0xf bank_mask:0xa bound_ctrl:1
	v_add_f32_dpp v138, v142, v142 row_half_mirror row_mask:0xf bank_mask:0xa bound_ctrl:1
	v_add_f32_dpp v139, v144, v144 row_half_mirror row_mask:0xf bank_mask:0xa bound_ctrl:1
	v_add_f32_dpp v136, v136, v136 quad_perm:[2,3,0,1] row_mask:0xf bank_mask:0xf bound_ctrl:1
	v_add_f32_dpp v138, v138, v138 quad_perm:[2,3,0,1] row_mask:0xf bank_mask:0xf bound_ctrl:1
	v_add_f32_dpp v137, v137, v137 quad_perm:[2,3,0,1] row_mask:0xf bank_mask:0xf bound_ctrl:1
	v_add_f32_dpp v139, v139, v139 quad_perm:[2,3,0,1] row_mask:0xf bank_mask:0xf bound_ctrl:1
	v_cndmask_b32_e64 v173, v155, v146, s[28:29]
	v_cndmask_b32_e64 v178, v157, v156, s[28:29]
	v_cndmask_b32_e64 v136, v136, v138, s[24:25]
	v_cndmask_b32_e64 v137, v137, v139, s[24:25]
	v_cndmask_b32_e64 v173, v178, v173, s[24:25]
	v_add_f32_e32 v146, v157, v167
	v_add_f32_dpp v136, v136, v136 quad_perm:[1,0,3,2] row_mask:0xf bank_mask:0xf bound_ctrl:1
	v_add_f32_dpp v137, v137, v137 quad_perm:[1,0,3,2] row_mask:0xf bank_mask:0xf bound_ctrl:1
	v_cndmask_b32_e64 v136, v136, v137, s[28:29]
	v_fmac_f32_e32 v136, 0x3fb8aa3b, v173
	s_nop 1
	v_max_f32_dpp v179, v136, v136 quad_perm:[1,0,3,2] row_mask:0xf bank_mask:0xf bound_ctrl:1
	s_nop 1
	v_max_f32_dpp v180, v179, v179 quad_perm:[2,3,0,1] row_mask:0xf bank_mask:0xf bound_ctrl:1
	v_max_f32_e32 v180, v134, v180
	v_sub_f32_e32 v155, v134, v180
	v_sub_f32_e32 v156, v136, v180
	v_mov_b32_e32 v134, v180
	v_exp_f32_e32 v155, v155
	v_exp_f32_e32 v156, v156
	s_nop 0
	v_mov_b32_dpp v137, v155 row_newbcast:0 row_mask:0xf bank_mask:0xf
	v_mov_b32_dpp v142, v155 row_newbcast:4 row_mask:0xf bank_mask:0xf
	v_mov_b32_dpp v150, v155 row_newbcast:8 row_mask:0xf bank_mask:0xf
	v_mov_b32_dpp v178, v155 row_newbcast:12 row_mask:0xf bank_mask:0xf
	v_add_f32_dpp v157, v156, v156 quad_perm:[1,0,3,2] row_mask:0xf bank_mask:0xf bound_ctrl:1
	v_mov_b32_dpp v138, v156 row_newbcast:0 row_mask:0xf bank_mask:0xf
	v_mov_b32_dpp v139, v156 row_newbcast:1 row_mask:0xf bank_mask:0xf
	v_mov_b32_dpp v140, v156 row_newbcast:2 row_mask:0xf bank_mask:0xf
	v_mov_b32_dpp v141, v156 row_newbcast:3 row_mask:0xf bank_mask:0xf
	v_add_f32_dpp v173, v157, v157 quad_perm:[2,3,0,1] row_mask:0xf bank_mask:0xf bound_ctrl:1
	v_mov_b32_dpp v144, v156 row_newbcast:4 row_mask:0xf bank_mask:0xf
	v_mov_b32_dpp v147, v156 row_newbcast:5 row_mask:0xf bank_mask:0xf
	v_mov_b32_dpp v148, v156 row_newbcast:6 row_mask:0xf bank_mask:0xf
	v_mov_b32_dpp v149, v156 row_newbcast:7 row_mask:0xf bank_mask:0xf
	v_fma_f32 v135, v135, v155, v173
	v_mov_b32_dpp v151, v156 row_newbcast:8 row_mask:0xf bank_mask:0xf
	v_mov_b32_dpp v152, v156 row_newbcast:9 row_mask:0xf bank_mask:0xf
	v_mov_b32_dpp v153, v156 row_newbcast:10 row_mask:0xf bank_mask:0xf
	v_mov_b32_dpp v154, v156 row_newbcast:11 row_mask:0xf bank_mask:0xf
	v_mov_b32_dpp v179, v156 row_newbcast:12 row_mask:0xf bank_mask:0xf
	v_mov_b32_dpp v180, v156 row_newbcast:13 row_mask:0xf bank_mask:0xf
	v_mov_b32_dpp v181, v156 row_newbcast:14 row_mask:0xf bank_mask:0xf
	v_mov_b32_dpp v0, v156 row_newbcast:15 row_mask:0xf bank_mask:0xf
	v_pk_mul_f32 v[118:119], v[118:119], v[136:137] op_sel:[0,1] op_sel_hi:[1,1]
	v_pk_mul_f32 v[120:121], v[120:121], v[136:137] op_sel:[0,1] op_sel_hi:[1,1]
	v_pk_mul_f32 v[122:123], v[122:123], v[142:143] op_sel:[0,0] op_sel_hi:[1,0]
	v_pk_mul_f32 v[124:125], v[124:125], v[142:143] op_sel:[0,0] op_sel_hi:[1,0]
	v_pk_mul_f32 v[126:127], v[126:127], v[150:151] op_sel:[0,0] op_sel_hi:[1,0]
	v_pk_mul_f32 v[128:129], v[128:129], v[150:151] op_sel:[0,0] op_sel_hi:[1,0]
	v_pk_mul_f32 v[130:131], v[130:131], v[178:179] op_sel:[0,0] op_sel_hi:[1,0]
	v_pk_mul_f32 v[132:133], v[132:133], v[178:179] op_sel:[0,0] op_sel_hi:[1,0]
	v_pk_fma_f32 v[118:119], v[138:139], v[22:23], v[118:119] op_sel:[0,0,0] op_sel_hi:[0,1,1]
	v_pk_fma_f32 v[120:121], v[138:139], v[24:25], v[120:121] op_sel:[0,0,0] op_sel_hi:[0,1,1]
	v_pk_fma_f32 v[122:123], v[144:145], v[22:23], v[122:123] op_sel:[0,0,0] op_sel_hi:[0,1,1]
	v_pk_fma_f32 v[124:125], v[144:145], v[24:25], v[124:125] op_sel:[0,0,0] op_sel_hi:[0,1,1]
	v_pk_fma_f32 v[126:127], v[150:151], v[22:23], v[126:127] op_sel:[1,0,0] op_sel_hi:[1,1,1]
	v_pk_fma_f32 v[128:129], v[150:151], v[24:25], v[128:129] op_sel:[1,0,0] op_sel_hi:[1,1,1]
	v_pk_fma_f32 v[130:131], v[178:179], v[22:23], v[130:131] op_sel:[1,0,0] op_sel_hi:[1,1,1]
	v_pk_fma_f32 v[132:133], v[178:179], v[24:25], v[132:133] op_sel:[1,0,0] op_sel_hi:[1,1,1]
	v_pk_fma_f32 v[118:119], v[138:139], v[18:19], v[118:119] op_sel:[1,0,0] op_sel_hi:[1,1,1]
	v_pk_fma_f32 v[120:121], v[138:139], v[20:21], v[120:121] op_sel:[1,0,0] op_sel_hi:[1,1,1]
	v_pk_fma_f32 v[122:123], v[146:147], v[18:19], v[122:123] op_sel:[1,0,0] op_sel_hi:[1,1,1]
	v_pk_fma_f32 v[124:125], v[146:147], v[20:21], v[124:125] op_sel:[1,0,0] op_sel_hi:[1,1,1]
	v_pk_fma_f32 v[126:127], v[152:153], v[18:19], v[126:127] op_sel:[0,0,0] op_sel_hi:[0,1,1]
	v_pk_fma_f32 v[128:129], v[152:153], v[20:21], v[128:129] op_sel:[0,0,0] op_sel_hi:[0,1,1]
	v_pk_fma_f32 v[130:131], v[180:181], v[18:19], v[130:131] op_sel:[0,0,0] op_sel_hi:[0,1,1]
	v_pk_fma_f32 v[132:133], v[180:181], v[20:21], v[132:133] op_sel:[0,0,0] op_sel_hi:[0,1,1]
	v_pk_fma_f32 v[118:119], v[140:141], v[26:27], v[118:119] op_sel:[0,0,0] op_sel_hi:[0,1,1]
	v_pk_fma_f32 v[120:121], v[140:141], v[28:29], v[120:121] op_sel:[0,0,0] op_sel_hi:[0,1,1]
	v_pk_fma_f32 v[122:123], v[148:149], v[26:27], v[122:123] op_sel:[0,0,0] op_sel_hi:[0,1,1]
	v_pk_fma_f32 v[124:125], v[148:149], v[28:29], v[124:125] op_sel:[0,0,0] op_sel_hi:[0,1,1]
	v_pk_fma_f32 v[126:127], v[152:153], v[26:27], v[126:127] op_sel:[1,0,0] op_sel_hi:[1,1,1]
	v_pk_fma_f32 v[128:129], v[152:153], v[28:29], v[128:129] op_sel:[1,0,0] op_sel_hi:[1,1,1]
	v_pk_fma_f32 v[130:131], v[180:181], v[26:27], v[130:131] op_sel:[1,0,0] op_sel_hi:[1,1,1]
	v_pk_fma_f32 v[132:133], v[180:181], v[28:29], v[132:133] op_sel:[1,0,0] op_sel_hi:[1,1,1]
	v_pk_fma_f32 v[118:119], v[140:141], v[30:31], v[118:119] op_sel:[1,0,0] op_sel_hi:[1,1,1]
	v_pk_fma_f32 v[120:121], v[140:141], v[32:33], v[120:121] op_sel:[1,0,0] op_sel_hi:[1,1,1]
	v_pk_fma_f32 v[122:123], v[148:149], v[30:31], v[122:123] op_sel:[1,0,0] op_sel_hi:[1,1,1]
	v_pk_fma_f32 v[124:125], v[148:149], v[32:33], v[124:125] op_sel:[1,0,0] op_sel_hi:[1,1,1]
	v_pk_fma_f32 v[126:127], v[154:155], v[30:31], v[126:127] op_sel:[0,0,0] op_sel_hi:[0,1,1]
	v_pk_fma_f32 v[128:129], v[154:155], v[32:33], v[128:129] op_sel:[0,0,0] op_sel_hi:[0,1,1]
	v_pk_fma_f32 v[130:131], v[0:1], v[30:31], v[130:131] op_sel:[0,0,0] op_sel_hi:[0,1,1]
	v_pk_fma_f32 v[132:133], v[0:1], v[32:33], v[132:133] op_sel:[0,0,0] op_sel_hi:[0,1,1]
	s_add_i32 s0, s8, 0x2000
	s_mov_b32 s6, s14
	s_mov_b32 s7, s15
	buffer_load_dwordx4 v[50:53], v161, s[12:15], s0 offen sc0 sc1 nt
	buffer_load_dwordx4 v[22:25], v161, s[4:7], s0 offen sc0 sc1 nt
	s_add_i32 s0, s3, 0x80
	buffer_load_dword v167, v162, s[16:19], s0 offen
	s_add_i32 s0, s8, 0x2400
	buffer_load_dwordx4 v[58:61], v161, s[12:15], s0 offen sc0 sc1 nt
	buffer_load_dwordx4 v[18:21], v161, s[4:7], s0 offen sc0 sc1 nt
	s_add_i32 s0, s3, 0x90
	buffer_load_dword v169, v162, s[16:19], s0 offen
	s_add_i32 s0, s8, 0x2800
	buffer_load_dwordx4 v[54:57], v161, s[12:15], s0 offen sc0 sc1 nt
	buffer_load_dwordx4 v[26:29], v161, s[4:7], s0 offen sc0 sc1 nt
	s_add_i32 s0, s3, 0xa0
	buffer_load_dword v170, v162, s[16:19], s0 offen
	s_add_i32 s0, s8, 0x2c00
	buffer_load_dwordx4 v[62:65], v161, s[12:15], s0 offen sc0 sc1 nt
	buffer_load_dwordx4 v[30:33], v161, s[4:7], s0 offen sc0 sc1 nt
	s_add_i32 s0, s3, 0xb0
	buffer_load_dword v171, v162, s[16:19], s0 offen
	s_waitcnt vmcnt(24)
	v_pk_mul_f32 v[98:99], v[116:117], v[36:37]
	v_pk_mul_f32 v[100:101], v[116:117], v[44:45]
	v_pk_mul_f32 v[174:175], v[116:117], v[40:41]
	v_pk_mul_f32 v[176:177], v[116:117], v[48:49]
	v_pk_fma_f32 v[98:99], v[114:115], v[34:35], v[98:99]
	v_pk_fma_f32 v[100:101], v[114:115], v[42:43], v[100:101]
	v_pk_fma_f32 v[174:175], v[114:115], v[38:39], v[174:175]
	v_pk_fma_f32 v[176:177], v[114:115], v[46:47], v[176:177]
	v_add_f32_e32 v136, v98, v99
	v_add_f32_e32 v137, v100, v101
	v_add_f32_e32 v138, v174, v175
	v_add_f32_e32 v139, v176, v177
	v_pk_mul_f32 v[98:99], v[112:113], v[36:37]
	v_pk_mul_f32 v[100:101], v[112:113], v[44:45]
	v_pk_mul_f32 v[174:175], v[112:113], v[40:41]
	v_pk_mul_f32 v[176:177], v[112:113], v[48:49]
	v_pk_fma_f32 v[98:99], v[110:111], v[34:35], v[98:99]
	v_pk_fma_f32 v[100:101], v[110:111], v[42:43], v[100:101]
	v_pk_fma_f32 v[174:175], v[110:111], v[38:39], v[174:175]
	v_pk_fma_f32 v[176:177], v[110:111], v[46:47], v[176:177]
	v_add_f32_e32 v140, v98, v99
	v_add_f32_e32 v141, v100, v101
	v_add_f32_e32 v142, v174, v175
	v_add_f32_e32 v144, v176, v177
	v_pk_mul_f32 v[98:99], v[108:109], v[36:37]
	v_pk_mul_f32 v[100:101], v[108:109], v[44:45]
	v_pk_mul_f32 v[174:175], v[108:109], v[40:41]
	v_pk_mul_f32 v[176:177], v[108:109], v[48:49]
	v_pk_fma_f32 v[98:99], v[106:107], v[34:35], v[98:99]
	v_pk_fma_f32 v[100:101], v[106:107], v[42:43], v[100:101]
	v_pk_fma_f32 v[174:175], v[106:107], v[38:39], v[174:175]
	v_pk_fma_f32 v[176:177], v[106:107], v[46:47], v[176:177]
	v_add_f32_e32 v147, v98, v99
	v_add_f32_e32 v148, v100, v101
	v_add_f32_e32 v149, v174, v175
	v_add_f32_e32 v150, v176, v177
	v_pk_mul_f32 v[98:99], v[104:105], v[36:37]
	v_pk_mul_f32 v[100:101], v[104:105], v[44:45]
	v_pk_mul_f32 v[174:175], v[104:105], v[40:41]
	v_pk_mul_f32 v[176:177], v[104:105], v[48:49]
	v_pk_fma_f32 v[98:99], v[102:103], v[34:35], v[98:99]
	v_pk_fma_f32 v[100:101], v[102:103], v[42:43], v[100:101]
	v_pk_fma_f32 v[174:175], v[102:103], v[38:39], v[174:175]
	v_pk_fma_f32 v[176:177], v[102:103], v[46:47], v[176:177]
	v_add_f32_e32 v151, v98, v99
	v_add_f32_e32 v152, v100, v101
	v_add_f32_e32 v153, v174, v175
	v_add_f32_e32 v154, v176, v177
	v_add_f32_e32 v155, v146, v166
	v_add_f32_e32 v156, v155, v165
	v_add_f32_e32 v157, v156, v164
	v_add_f32_dpp v136, v136, v136 row_mirror row_mask:0xf bank_mask:0x3 bound_ctrl:1
	v_add_f32_dpp v137, v137, v137 row_mirror row_mask:0xf bank_mask:0x3 bound_ctrl:1
	v_add_f32_dpp v138, v138, v138 row_mirror row_mask:0xf bank_mask:0x3 bound_ctrl:1
	v_add_f32_dpp v139, v139, v139 row_mirror row_mask:0xf bank_mask:0x3 bound_ctrl:1
	v_add_f32_dpp v140, v140, v140 row_mirror row_mask:0xf bank_mask:0x3 bound_ctrl:1
	v_add_f32_dpp v141, v141, v141 row_mirror row_mask:0xf bank_mask:0x3 bound_ctrl:1
	v_add_f32_dpp v142, v142, v142 row_mirror row_mask:0xf bank_mask:0x3 bound_ctrl:1
	v_add_f32_dpp v144, v144, v144 row_mirror row_mask:0xf bank_mask:0x3 bound_ctrl:1
	v_add_f32_dpp v136, v147, v147 row_mirror row_mask:0xf bank_mask:0xc bound_ctrl:1
	v_add_f32_dpp v137, v148, v148 row_mirror row_mask:0xf bank_mask:0xc bound_ctrl:1
	v_add_f32_dpp v138, v149, v149 row_mirror row_mask:0xf bank_mask:0xc bound_ctrl:1
	v_add_f32_dpp v139, v150, v150 row_mirror row_mask:0xf bank_mask:0xc bound_ctrl:1
	v_add_f32_dpp v140, v151, v151 row_mirror row_mask:0xf bank_mask:0xc bound_ctrl:1
	v_add_f32_dpp v141, v152, v152 row_mirror row_mask:0xf bank_mask:0xc bound_ctrl:1
	v_add_f32_dpp v142, v153, v153 row_mirror row_mask:0xf bank_mask:0xc bound_ctrl:1
	v_add_f32_dpp v144, v154, v154 row_mirror row_mask:0xf bank_mask:0xc bound_ctrl:1
	v_add_f32_dpp v136, v136, v136 row_half_mirror row_mask:0xf bank_mask:0x5 bound_ctrl:1
	v_add_f32_dpp v137, v137, v137 row_half_mirror row_mask:0xf bank_mask:0x5 bound_ctrl:1
	v_add_f32_dpp v138, v138, v138 row_half_mirror row_mask:0xf bank_mask:0x5 bound_ctrl:1
	v_add_f32_dpp v139, v139, v139 row_half_mirror row_mask:0xf bank_mask:0x5 bound_ctrl:1
	v_add_f32_dpp v136, v140, v140 row_half_mirror row_mask:0xf bank_mask:0xa bound_ctrl:1
	v_add_f32_dpp v137, v141, v141 row_half_mirror row_mask:0xf bank_mask:0xa bound_ctrl:1
	v_add_f32_dpp v138, v142, v142 row_half_mirror row_mask:0xf bank_mask:0xa bound_ctrl:1
	v_add_f32_dpp v139, v144, v144 row_half_mirror row_mask:0xf bank_mask:0xa bound_ctrl:1
	v_add_f32_dpp v136, v136, v136 quad_perm:[2,3,0,1] row_mask:0xf bank_mask:0xf bound_ctrl:1
	v_add_f32_dpp v138, v138, v138 quad_perm:[2,3,0,1] row_mask:0xf bank_mask:0xf bound_ctrl:1
	v_add_f32_dpp v137, v137, v137 quad_perm:[2,3,0,1] row_mask:0xf bank_mask:0xf bound_ctrl:1
	v_add_f32_dpp v139, v139, v139 quad_perm:[2,3,0,1] row_mask:0xf bank_mask:0xf bound_ctrl:1
	v_cndmask_b32_e64 v173, v155, v146, s[28:29]
	v_cndmask_b32_e64 v178, v157, v156, s[28:29]
	v_cndmask_b32_e64 v136, v136, v138, s[24:25]
	v_cndmask_b32_e64 v137, v137, v139, s[24:25]
	v_cndmask_b32_e64 v173, v178, v173, s[24:25]
	v_add_f32_e32 v146, v157, v168
	v_add_f32_dpp v136, v136, v136 quad_perm:[1,0,3,2] row_mask:0xf bank_mask:0xf bound_ctrl:1
	v_add_f32_dpp v137, v137, v137 quad_perm:[1,0,3,2] row_mask:0xf bank_mask:0xf bound_ctrl:1
	v_cndmask_b32_e64 v136, v136, v137, s[28:29]
	v_fmac_f32_e32 v136, 0x3fb8aa3b, v173
	s_nop 1
	v_max_f32_dpp v179, v136, v136 quad_perm:[1,0,3,2] row_mask:0xf bank_mask:0xf bound_ctrl:1
	s_nop 1
	v_max_f32_dpp v180, v179, v179 quad_perm:[2,3,0,1] row_mask:0xf bank_mask:0xf bound_ctrl:1
	v_max_f32_e32 v180, v134, v180
	v_sub_f32_e32 v155, v134, v180
	v_sub_f32_e32 v156, v136, v180
	v_mov_b32_e32 v134, v180
	v_exp_f32_e32 v155, v155
	v_exp_f32_e32 v156, v156
	s_nop 0
	v_mov_b32_dpp v137, v155 row_newbcast:0 row_mask:0xf bank_mask:0xf
	v_mov_b32_dpp v142, v155 row_newbcast:4 row_mask:0xf bank_mask:0xf
	v_mov_b32_dpp v150, v155 row_newbcast:8 row_mask:0xf bank_mask:0xf
	v_mov_b32_dpp v178, v155 row_newbcast:12 row_mask:0xf bank_mask:0xf
	v_add_f32_dpp v157, v156, v156 quad_perm:[1,0,3,2] row_mask:0xf bank_mask:0xf bound_ctrl:1
	v_mov_b32_dpp v138, v156 row_newbcast:0 row_mask:0xf bank_mask:0xf
	v_mov_b32_dpp v139, v156 row_newbcast:1 row_mask:0xf bank_mask:0xf
	v_mov_b32_dpp v140, v156 row_newbcast:2 row_mask:0xf bank_mask:0xf
	v_mov_b32_dpp v141, v156 row_newbcast:3 row_mask:0xf bank_mask:0xf
	v_add_f32_dpp v173, v157, v157 quad_perm:[2,3,0,1] row_mask:0xf bank_mask:0xf bound_ctrl:1
	v_mov_b32_dpp v144, v156 row_newbcast:4 row_mask:0xf bank_mask:0xf
	v_mov_b32_dpp v147, v156 row_newbcast:5 row_mask:0xf bank_mask:0xf
	v_mov_b32_dpp v148, v156 row_newbcast:6 row_mask:0xf bank_mask:0xf
	v_mov_b32_dpp v149, v156 row_newbcast:7 row_mask:0xf bank_mask:0xf
	v_fma_f32 v135, v135, v155, v173
	v_mov_b32_dpp v151, v156 row_newbcast:8 row_mask:0xf bank_mask:0xf
	v_mov_b32_dpp v152, v156 row_newbcast:9 row_mask:0xf bank_mask:0xf
	v_mov_b32_dpp v153, v156 row_newbcast:10 row_mask:0xf bank_mask:0xf
	v_mov_b32_dpp v154, v156 row_newbcast:11 row_mask:0xf bank_mask:0xf
	v_mov_b32_dpp v179, v156 row_newbcast:12 row_mask:0xf bank_mask:0xf
	v_mov_b32_dpp v180, v156 row_newbcast:13 row_mask:0xf bank_mask:0xf
	v_mov_b32_dpp v181, v156 row_newbcast:14 row_mask:0xf bank_mask:0xf
	v_mov_b32_dpp v0, v156 row_newbcast:15 row_mask:0xf bank_mask:0xf
	v_pk_mul_f32 v[118:119], v[118:119], v[136:137] op_sel:[0,1] op_sel_hi:[1,1]
	v_pk_mul_f32 v[120:121], v[120:121], v[136:137] op_sel:[0,1] op_sel_hi:[1,1]
	v_pk_mul_f32 v[122:123], v[122:123], v[142:143] op_sel:[0,0] op_sel_hi:[1,0]
	v_pk_mul_f32 v[124:125], v[124:125], v[142:143] op_sel:[0,0] op_sel_hi:[1,0]
	v_pk_mul_f32 v[126:127], v[126:127], v[150:151] op_sel:[0,0] op_sel_hi:[1,0]
	v_pk_mul_f32 v[128:129], v[128:129], v[150:151] op_sel:[0,0] op_sel_hi:[1,0]
	v_pk_mul_f32 v[130:131], v[130:131], v[178:179] op_sel:[0,0] op_sel_hi:[1,0]
	v_pk_mul_f32 v[132:133], v[132:133], v[178:179] op_sel:[0,0] op_sel_hi:[1,0]
	v_pk_fma_f32 v[118:119], v[138:139], v[2:3], v[118:119] op_sel:[0,0,0] op_sel_hi:[0,1,1]
	v_pk_fma_f32 v[120:121], v[138:139], v[4:5], v[120:121] op_sel:[0,0,0] op_sel_hi:[0,1,1]
	v_pk_fma_f32 v[122:123], v[144:145], v[2:3], v[122:123] op_sel:[0,0,0] op_sel_hi:[0,1,1]
	v_pk_fma_f32 v[124:125], v[144:145], v[4:5], v[124:125] op_sel:[0,0,0] op_sel_hi:[0,1,1]
	v_pk_fma_f32 v[126:127], v[150:151], v[2:3], v[126:127] op_sel:[1,0,0] op_sel_hi:[1,1,1]
	v_pk_fma_f32 v[128:129], v[150:151], v[4:5], v[128:129] op_sel:[1,0,0] op_sel_hi:[1,1,1]
	v_pk_fma_f32 v[130:131], v[178:179], v[2:3], v[130:131] op_sel:[1,0,0] op_sel_hi:[1,1,1]
	v_pk_fma_f32 v[132:133], v[178:179], v[4:5], v[132:133] op_sel:[1,0,0] op_sel_hi:[1,1,1]
	v_pk_fma_f32 v[118:119], v[138:139], v[6:7], v[118:119] op_sel:[1,0,0] op_sel_hi:[1,1,1]
	v_pk_fma_f32 v[120:121], v[138:139], v[8:9], v[120:121] op_sel:[1,0,0] op_sel_hi:[1,1,1]
	v_pk_fma_f32 v[122:123], v[146:147], v[6:7], v[122:123] op_sel:[1,0,0] op_sel_hi:[1,1,1]
	v_pk_fma_f32 v[124:125], v[146:147], v[8:9], v[124:125] op_sel:[1,0,0] op_sel_hi:[1,1,1]
	v_pk_fma_f32 v[126:127], v[152:153], v[6:7], v[126:127] op_sel:[0,0,0] op_sel_hi:[0,1,1]
	v_pk_fma_f32 v[128:129], v[152:153], v[8:9], v[128:129] op_sel:[0,0,0] op_sel_hi:[0,1,1]
	v_pk_fma_f32 v[130:131], v[180:181], v[6:7], v[130:131] op_sel:[0,0,0] op_sel_hi:[0,1,1]
	v_pk_fma_f32 v[132:133], v[180:181], v[8:9], v[132:133] op_sel:[0,0,0] op_sel_hi:[0,1,1]
	v_pk_fma_f32 v[118:119], v[140:141], v[10:11], v[118:119] op_sel:[0,0,0] op_sel_hi:[0,1,1]
	v_pk_fma_f32 v[120:121], v[140:141], v[12:13], v[120:121] op_sel:[0,0,0] op_sel_hi:[0,1,1]
	v_pk_fma_f32 v[122:123], v[148:149], v[10:11], v[122:123] op_sel:[0,0,0] op_sel_hi:[0,1,1]
	v_pk_fma_f32 v[124:125], v[148:149], v[12:13], v[124:125] op_sel:[0,0,0] op_sel_hi:[0,1,1]
	v_pk_fma_f32 v[126:127], v[152:153], v[10:11], v[126:127] op_sel:[1,0,0] op_sel_hi:[1,1,1]
	v_pk_fma_f32 v[128:129], v[152:153], v[12:13], v[128:129] op_sel:[1,0,0] op_sel_hi:[1,1,1]
	v_pk_fma_f32 v[130:131], v[180:181], v[10:11], v[130:131] op_sel:[1,0,0] op_sel_hi:[1,1,1]
	v_pk_fma_f32 v[132:133], v[180:181], v[12:13], v[132:133] op_sel:[1,0,0] op_sel_hi:[1,1,1]
	v_pk_fma_f32 v[118:119], v[140:141], v[14:15], v[118:119] op_sel:[1,0,0] op_sel_hi:[1,1,1]
	v_pk_fma_f32 v[120:121], v[140:141], v[16:17], v[120:121] op_sel:[1,0,0] op_sel_hi:[1,1,1]
	v_pk_fma_f32 v[122:123], v[148:149], v[14:15], v[122:123] op_sel:[1,0,0] op_sel_hi:[1,1,1]
	v_pk_fma_f32 v[124:125], v[148:149], v[16:17], v[124:125] op_sel:[1,0,0] op_sel_hi:[1,1,1]
	v_pk_fma_f32 v[126:127], v[154:155], v[14:15], v[126:127] op_sel:[0,0,0] op_sel_hi:[0,1,1]
	v_pk_fma_f32 v[128:129], v[154:155], v[16:17], v[128:129] op_sel:[0,0,0] op_sel_hi:[0,1,1]
	v_pk_fma_f32 v[130:131], v[0:1], v[14:15], v[130:131] op_sel:[0,0,0] op_sel_hi:[0,1,1]
	v_pk_fma_f32 v[132:133], v[0:1], v[16:17], v[132:133] op_sel:[0,0,0] op_sel_hi:[0,1,1]
	s_add_i32 s0, s8, 0x1000
	buffer_load_dwordx4 v[34:37], v161, s[12:15], s0 offen sc0 sc1 nt
	buffer_load_dwordx4 v[2:5], v161, s[4:7], s0 offen sc0 sc1 nt
	s_add_i32 s0, s3, 64
	buffer_load_dword v168, v162, s[16:19], s0 offen
	s_add_i32 s0, s8, 0x1400
	buffer_load_dwordx4 v[42:45], v161, s[12:15], s0 offen sc0 sc1 nt
	buffer_load_dwordx4 v[6:9], v161, s[4:7], s0 offen sc0 sc1 nt
	s_add_i32 s0, s3, 0x50
	buffer_load_dword v164, v162, s[16:19], s0 offen
	s_add_i32 s0, s8, 0x1800
	buffer_load_dwordx4 v[38:41], v161, s[12:15], s0 offen sc0 sc1 nt
	buffer_load_dwordx4 v[10:13], v161, s[4:7], s0 offen sc0 sc1 nt
	s_add_i32 s0, s3, 0x60
	buffer_load_dword v165, v162, s[16:19], s0 offen
	s_add_i32 s0, s8, 0x1c00
	buffer_load_dwordx4 v[46:49], v161, s[12:15], s0 offen sc0 sc1 nt
	buffer_load_dwordx4 v[14:17], v161, s[4:7], s0 offen sc0 sc1 nt
	s_add_i32 s0, s3, 0x70
	buffer_load_dword v166, v162, s[16:19], s0 offen
	s_waitcnt vmcnt(24)
	v_pk_mul_f32 v[98:99], v[116:117], v[84:85]
	v_pk_mul_f32 v[100:101], v[116:117], v[88:89]
	v_pk_mul_f32 v[174:175], v[116:117], v[92:93]
	v_pk_mul_f32 v[176:177], v[116:117], v[96:97]
	v_pk_fma_f32 v[98:99], v[114:115], v[82:83], v[98:99]
	v_pk_fma_f32 v[100:101], v[114:115], v[86:87], v[100:101]
	v_pk_fma_f32 v[174:175], v[114:115], v[90:91], v[174:175]
	v_pk_fma_f32 v[176:177], v[114:115], v[94:95], v[176:177]
	v_add_f32_e32 v136, v98, v99
	v_add_f32_e32 v137, v100, v101
	v_add_f32_e32 v138, v174, v175
	v_add_f32_e32 v139, v176, v177
	v_pk_mul_f32 v[98:99], v[112:113], v[84:85]
	v_pk_mul_f32 v[100:101], v[112:113], v[88:89]
	v_pk_mul_f32 v[174:175], v[112:113], v[92:93]
	v_pk_mul_f32 v[176:177], v[112:113], v[96:97]
	v_pk_fma_f32 v[98:99], v[110:111], v[82:83], v[98:99]
	v_pk_fma_f32 v[100:101], v[110:111], v[86:87], v[100:101]
	v_pk_fma_f32 v[174:175], v[110:111], v[90:91], v[174:175]
	v_pk_fma_f32 v[176:177], v[110:111], v[94:95], v[176:177]
	v_add_f32_e32 v140, v98, v99
	v_add_f32_e32 v141, v100, v101
	v_add_f32_e32 v142, v174, v175
	v_add_f32_e32 v144, v176, v177
	v_pk_mul_f32 v[98:99], v[108:109], v[84:85]
	v_pk_mul_f32 v[100:101], v[108:109], v[88:89]
	v_pk_mul_f32 v[174:175], v[108:109], v[92:93]
	v_pk_mul_f32 v[176:177], v[108:109], v[96:97]
	v_pk_fma_f32 v[98:99], v[106:107], v[82:83], v[98:99]
	v_pk_fma_f32 v[100:101], v[106:107], v[86:87], v[100:101]
	v_pk_fma_f32 v[174:175], v[106:107], v[90:91], v[174:175]
	v_pk_fma_f32 v[176:177], v[106:107], v[94:95], v[176:177]
	v_add_f32_e32 v147, v98, v99
	v_add_f32_e32 v148, v100, v101
	v_add_f32_e32 v149, v174, v175
	v_add_f32_e32 v150, v176, v177
	v_pk_mul_f32 v[98:99], v[104:105], v[84:85]
	v_pk_mul_f32 v[100:101], v[104:105], v[88:89]
	v_pk_mul_f32 v[174:175], v[104:105], v[92:93]
	v_pk_mul_f32 v[176:177], v[104:105], v[96:97]
	v_pk_fma_f32 v[98:99], v[102:103], v[82:83], v[98:99]
	v_pk_fma_f32 v[100:101], v[102:103], v[86:87], v[100:101]
	v_pk_fma_f32 v[174:175], v[102:103], v[90:91], v[174:175]
	v_pk_fma_f32 v[176:177], v[102:103], v[94:95], v[176:177]
	v_add_f32_e32 v151, v98, v99
	v_add_f32_e32 v152, v100, v101
	v_add_f32_e32 v153, v174, v175
	v_add_f32_e32 v154, v176, v177
	v_add_f32_e32 v155, v146, v172
	v_add_f32_e32 v156, v155, v145
	v_add_f32_e32 v157, v156, v143
	v_add_f32_dpp v136, v136, v136 row_mirror row_mask:0xf bank_mask:0x3 bound_ctrl:1
	v_add_f32_dpp v137, v137, v137 row_mirror row_mask:0xf bank_mask:0x3 bound_ctrl:1
	v_add_f32_dpp v138, v138, v138 row_mirror row_mask:0xf bank_mask:0x3 bound_ctrl:1
	v_add_f32_dpp v139, v139, v139 row_mirror row_mask:0xf bank_mask:0x3 bound_ctrl:1
	v_add_f32_dpp v140, v140, v140 row_mirror row_mask:0xf bank_mask:0x3 bound_ctrl:1
	v_add_f32_dpp v141, v141, v141 row_mirror row_mask:0xf bank_mask:0x3 bound_ctrl:1
	v_add_f32_dpp v142, v142, v142 row_mirror row_mask:0xf bank_mask:0x3 bound_ctrl:1
	v_add_f32_dpp v144, v144, v144 row_mirror row_mask:0xf bank_mask:0x3 bound_ctrl:1
	v_add_f32_dpp v136, v147, v147 row_mirror row_mask:0xf bank_mask:0xc bound_ctrl:1
	v_add_f32_dpp v137, v148, v148 row_mirror row_mask:0xf bank_mask:0xc bound_ctrl:1
	v_add_f32_dpp v138, v149, v149 row_mirror row_mask:0xf bank_mask:0xc bound_ctrl:1
	v_add_f32_dpp v139, v150, v150 row_mirror row_mask:0xf bank_mask:0xc bound_ctrl:1
	v_add_f32_dpp v140, v151, v151 row_mirror row_mask:0xf bank_mask:0xc bound_ctrl:1
	v_add_f32_dpp v141, v152, v152 row_mirror row_mask:0xf bank_mask:0xc bound_ctrl:1
	v_add_f32_dpp v142, v153, v153 row_mirror row_mask:0xf bank_mask:0xc bound_ctrl:1
	v_add_f32_dpp v144, v154, v154 row_mirror row_mask:0xf bank_mask:0xc bound_ctrl:1
	v_add_f32_dpp v136, v136, v136 row_half_mirror row_mask:0xf bank_mask:0x5 bound_ctrl:1
	v_add_f32_dpp v137, v137, v137 row_half_mirror row_mask:0xf bank_mask:0x5 bound_ctrl:1
	v_add_f32_dpp v138, v138, v138 row_half_mirror row_mask:0xf bank_mask:0x5 bound_ctrl:1
	v_add_f32_dpp v139, v139, v139 row_half_mirror row_mask:0xf bank_mask:0x5 bound_ctrl:1
	v_add_f32_dpp v136, v140, v140 row_half_mirror row_mask:0xf bank_mask:0xa bound_ctrl:1
	v_add_f32_dpp v137, v141, v141 row_half_mirror row_mask:0xf bank_mask:0xa bound_ctrl:1
	v_add_f32_dpp v138, v142, v142 row_half_mirror row_mask:0xf bank_mask:0xa bound_ctrl:1
	v_add_f32_dpp v139, v144, v144 row_half_mirror row_mask:0xf bank_mask:0xa bound_ctrl:1
	v_add_f32_dpp v136, v136, v136 quad_perm:[2,3,0,1] row_mask:0xf bank_mask:0xf bound_ctrl:1
	v_add_f32_dpp v138, v138, v138 quad_perm:[2,3,0,1] row_mask:0xf bank_mask:0xf bound_ctrl:1
	v_add_f32_dpp v137, v137, v137 quad_perm:[2,3,0,1] row_mask:0xf bank_mask:0xf bound_ctrl:1
	v_add_f32_dpp v139, v139, v139 quad_perm:[2,3,0,1] row_mask:0xf bank_mask:0xf bound_ctrl:1
	v_cndmask_b32_e64 v173, v155, v146, s[28:29]
	v_cndmask_b32_e64 v178, v157, v156, s[28:29]
	v_cndmask_b32_e64 v136, v136, v138, s[24:25]
	v_cndmask_b32_e64 v137, v137, v139, s[24:25]
	v_cndmask_b32_e64 v173, v178, v173, s[24:25]
	v_add_f32_e32 v146, v157, v163
	v_add_f32_dpp v136, v136, v136 quad_perm:[1,0,3,2] row_mask:0xf bank_mask:0xf bound_ctrl:1
	v_add_f32_dpp v137, v137, v137 quad_perm:[1,0,3,2] row_mask:0xf bank_mask:0xf bound_ctrl:1
	v_cndmask_b32_e64 v136, v136, v137, s[28:29]
	v_fmac_f32_e32 v136, 0x3fb8aa3b, v173
	s_nop 1
	v_max_f32_dpp v179, v136, v136 quad_perm:[1,0,3,2] row_mask:0xf bank_mask:0xf bound_ctrl:1
	s_nop 1
	v_max_f32_dpp v180, v179, v179 quad_perm:[2,3,0,1] row_mask:0xf bank_mask:0xf bound_ctrl:1
	v_max_f32_e32 v180, v134, v180
	v_sub_f32_e32 v155, v134, v180
	v_sub_f32_e32 v156, v136, v180
	v_mov_b32_e32 v134, v180
	v_exp_f32_e32 v155, v155
	v_exp_f32_e32 v156, v156
	s_nop 0
	v_mov_b32_dpp v137, v155 row_newbcast:0 row_mask:0xf bank_mask:0xf
	v_mov_b32_dpp v142, v155 row_newbcast:4 row_mask:0xf bank_mask:0xf
	v_mov_b32_dpp v150, v155 row_newbcast:8 row_mask:0xf bank_mask:0xf
	v_mov_b32_dpp v178, v155 row_newbcast:12 row_mask:0xf bank_mask:0xf
	v_add_f32_dpp v157, v156, v156 quad_perm:[1,0,3,2] row_mask:0xf bank_mask:0xf bound_ctrl:1
	v_mov_b32_dpp v138, v156 row_newbcast:0 row_mask:0xf bank_mask:0xf
	v_mov_b32_dpp v139, v156 row_newbcast:1 row_mask:0xf bank_mask:0xf
	v_mov_b32_dpp v140, v156 row_newbcast:2 row_mask:0xf bank_mask:0xf
	v_mov_b32_dpp v141, v156 row_newbcast:3 row_mask:0xf bank_mask:0xf
	v_add_f32_dpp v173, v157, v157 quad_perm:[2,3,0,1] row_mask:0xf bank_mask:0xf bound_ctrl:1
	v_mov_b32_dpp v144, v156 row_newbcast:4 row_mask:0xf bank_mask:0xf
	v_mov_b32_dpp v147, v156 row_newbcast:5 row_mask:0xf bank_mask:0xf
	v_mov_b32_dpp v148, v156 row_newbcast:6 row_mask:0xf bank_mask:0xf
	v_mov_b32_dpp v149, v156 row_newbcast:7 row_mask:0xf bank_mask:0xf
	v_fma_f32 v135, v135, v155, v173
	v_mov_b32_dpp v151, v156 row_newbcast:8 row_mask:0xf bank_mask:0xf
	v_mov_b32_dpp v152, v156 row_newbcast:9 row_mask:0xf bank_mask:0xf
	v_mov_b32_dpp v153, v156 row_newbcast:10 row_mask:0xf bank_mask:0xf
	v_mov_b32_dpp v154, v156 row_newbcast:11 row_mask:0xf bank_mask:0xf
	v_mov_b32_dpp v179, v156 row_newbcast:12 row_mask:0xf bank_mask:0xf
	v_mov_b32_dpp v180, v156 row_newbcast:13 row_mask:0xf bank_mask:0xf
	v_mov_b32_dpp v181, v156 row_newbcast:14 row_mask:0xf bank_mask:0xf
	v_mov_b32_dpp v0, v156 row_newbcast:15 row_mask:0xf bank_mask:0xf
	v_pk_mul_f32 v[118:119], v[118:119], v[136:137] op_sel:[0,1] op_sel_hi:[1,1]
	v_pk_mul_f32 v[120:121], v[120:121], v[136:137] op_sel:[0,1] op_sel_hi:[1,1]
	v_pk_mul_f32 v[122:123], v[122:123], v[142:143] op_sel:[0,0] op_sel_hi:[1,0]
	v_pk_mul_f32 v[124:125], v[124:125], v[142:143] op_sel:[0,0] op_sel_hi:[1,0]
	v_pk_mul_f32 v[126:127], v[126:127], v[150:151] op_sel:[0,0] op_sel_hi:[1,0]
	v_pk_mul_f32 v[128:129], v[128:129], v[150:151] op_sel:[0,0] op_sel_hi:[1,0]
	v_pk_mul_f32 v[130:131], v[130:131], v[178:179] op_sel:[0,0] op_sel_hi:[1,0]
	v_pk_mul_f32 v[132:133], v[132:133], v[178:179] op_sel:[0,0] op_sel_hi:[1,0]
	v_pk_fma_f32 v[118:119], v[138:139], v[66:67], v[118:119] op_sel:[0,0,0] op_sel_hi:[0,1,1]
	v_pk_fma_f32 v[120:121], v[138:139], v[68:69], v[120:121] op_sel:[0,0,0] op_sel_hi:[0,1,1]
	v_pk_fma_f32 v[122:123], v[144:145], v[66:67], v[122:123] op_sel:[0,0,0] op_sel_hi:[0,1,1]
	v_pk_fma_f32 v[124:125], v[144:145], v[68:69], v[124:125] op_sel:[0,0,0] op_sel_hi:[0,1,1]
	v_pk_fma_f32 v[126:127], v[150:151], v[66:67], v[126:127] op_sel:[1,0,0] op_sel_hi:[1,1,1]
	v_pk_fma_f32 v[128:129], v[150:151], v[68:69], v[128:129] op_sel:[1,0,0] op_sel_hi:[1,1,1]
	v_pk_fma_f32 v[130:131], v[178:179], v[66:67], v[130:131] op_sel:[1,0,0] op_sel_hi:[1,1,1]
	v_pk_fma_f32 v[132:133], v[178:179], v[68:69], v[132:133] op_sel:[1,0,0] op_sel_hi:[1,1,1]
	v_pk_fma_f32 v[118:119], v[138:139], v[70:71], v[118:119] op_sel:[1,0,0] op_sel_hi:[1,1,1]
	v_pk_fma_f32 v[120:121], v[138:139], v[72:73], v[120:121] op_sel:[1,0,0] op_sel_hi:[1,1,1]
	v_pk_fma_f32 v[122:123], v[146:147], v[70:71], v[122:123] op_sel:[1,0,0] op_sel_hi:[1,1,1]
	v_pk_fma_f32 v[124:125], v[146:147], v[72:73], v[124:125] op_sel:[1,0,0] op_sel_hi:[1,1,1]
	v_pk_fma_f32 v[126:127], v[152:153], v[70:71], v[126:127] op_sel:[0,0,0] op_sel_hi:[0,1,1]
	v_pk_fma_f32 v[128:129], v[152:153], v[72:73], v[128:129] op_sel:[0,0,0] op_sel_hi:[0,1,1]
	v_pk_fma_f32 v[130:131], v[180:181], v[70:71], v[130:131] op_sel:[0,0,0] op_sel_hi:[0,1,1]
	v_pk_fma_f32 v[132:133], v[180:181], v[72:73], v[132:133] op_sel:[0,0,0] op_sel_hi:[0,1,1]
	v_pk_fma_f32 v[118:119], v[140:141], v[74:75], v[118:119] op_sel:[0,0,0] op_sel_hi:[0,1,1]
	v_pk_fma_f32 v[120:121], v[140:141], v[76:77], v[120:121] op_sel:[0,0,0] op_sel_hi:[0,1,1]
	v_pk_fma_f32 v[122:123], v[148:149], v[74:75], v[122:123] op_sel:[0,0,0] op_sel_hi:[0,1,1]
	v_pk_fma_f32 v[124:125], v[148:149], v[76:77], v[124:125] op_sel:[0,0,0] op_sel_hi:[0,1,1]
	v_pk_fma_f32 v[126:127], v[152:153], v[74:75], v[126:127] op_sel:[1,0,0] op_sel_hi:[1,1,1]
	v_pk_fma_f32 v[128:129], v[152:153], v[76:77], v[128:129] op_sel:[1,0,0] op_sel_hi:[1,1,1]
	v_pk_fma_f32 v[130:131], v[180:181], v[74:75], v[130:131] op_sel:[1,0,0] op_sel_hi:[1,1,1]
	v_pk_fma_f32 v[132:133], v[180:181], v[76:77], v[132:133] op_sel:[1,0,0] op_sel_hi:[1,1,1]
	v_pk_fma_f32 v[118:119], v[140:141], v[78:79], v[118:119] op_sel:[1,0,0] op_sel_hi:[1,1,1]
	v_pk_fma_f32 v[120:121], v[140:141], v[80:81], v[120:121] op_sel:[1,0,0] op_sel_hi:[1,1,1]
	v_pk_fma_f32 v[122:123], v[148:149], v[78:79], v[122:123] op_sel:[1,0,0] op_sel_hi:[1,1,1]
	v_pk_fma_f32 v[124:125], v[148:149], v[80:81], v[124:125] op_sel:[1,0,0] op_sel_hi:[1,1,1]
	v_pk_fma_f32 v[126:127], v[154:155], v[78:79], v[126:127] op_sel:[0,0,0] op_sel_hi:[0,1,1]
	v_pk_fma_f32 v[128:129], v[154:155], v[80:81], v[128:129] op_sel:[0,0,0] op_sel_hi:[0,1,1]
	v_pk_fma_f32 v[130:131], v[0:1], v[78:79], v[130:131] op_sel:[0,0,0] op_sel_hi:[0,1,1]
	v_pk_fma_f32 v[132:133], v[0:1], v[80:81], v[132:133] op_sel:[0,0,0] op_sel_hi:[0,1,1]
	s_add_i32 s0, s8, 0x400
	buffer_load_dwordx4 v[82:85], v161, s[12:15], s8 offen sc0 sc1 nt
	buffer_load_dwordx4 v[66:69], v161, s[4:7], s8 offen sc0 sc1 nt
	buffer_load_dword v163, v162, s[16:19], s3 offen
	buffer_load_dwordx4 v[86:89], v161, s[12:15], s0 offen sc0 sc1 nt
	buffer_load_dwordx4 v[70:73], v161, s[4:7], s0 offen sc0 sc1 nt
	s_add_i32 s0, s3, 16
	buffer_load_dword v143, v162, s[16:19], s0 offen
	s_add_i32 s0, s8, 0x800
	buffer_load_dwordx4 v[90:93], v161, s[12:15], s0 offen sc0 sc1 nt
	buffer_load_dwordx4 v[74:77], v161, s[4:7], s0 offen sc0 sc1 nt
	s_add_i32 s0, s3, 32
	buffer_load_dword v145, v162, s[16:19], s0 offen
	s_add_i32 s0, s8, 0xc00
	buffer_load_dwordx4 v[94:97], v161, s[12:15], s0 offen sc0 sc1 nt
	buffer_load_dwordx4 v[78:81], v161, s[4:7], s0 offen sc0 sc1 nt
	s_add_i32 s0, s3, 48
	buffer_load_dword v172, v162, s[16:19], s0 offen
	s_add_i32 s2, s2, -12
	s_addk_i32 s3, 0xff40
	s_addk_i32 s8, 0xd000
	s_cmp_lt_u32 s2, 24
	s_cbranch_scc0 .Lpg_loop
	s_waitcnt vmcnt(24)
	v_pk_mul_f32 v[98:99], v[116:117], v[52:53]
	v_pk_mul_f32 v[100:101], v[116:117], v[60:61]
	v_pk_mul_f32 v[174:175], v[116:117], v[56:57]
	v_pk_mul_f32 v[176:177], v[116:117], v[64:65]
	v_pk_fma_f32 v[98:99], v[114:115], v[50:51], v[98:99]
	v_pk_fma_f32 v[100:101], v[114:115], v[58:59], v[100:101]
	v_pk_fma_f32 v[174:175], v[114:115], v[54:55], v[174:175]
	v_pk_fma_f32 v[176:177], v[114:115], v[62:63], v[176:177]
	v_add_f32_e32 v136, v98, v99
	v_add_f32_e32 v137, v100, v101
	v_add_f32_e32 v138, v174, v175
	v_add_f32_e32 v139, v176, v177
	v_pk_mul_f32 v[98:99], v[112:113], v[52:53]
	v_pk_mul_f32 v[100:101], v[112:113], v[60:61]
	v_pk_mul_f32 v[174:175], v[112:113], v[56:57]
	v_pk_mul_f32 v[176:177], v[112:113], v[64:65]
	v_pk_fma_f32 v[98:99], v[110:111], v[50:51], v[98:99]
	v_pk_fma_f32 v[100:101], v[110:111], v[58:59], v[100:101]
	v_pk_fma_f32 v[174:175], v[110:111], v[54:55], v[174:175]
	v_pk_fma_f32 v[176:177], v[110:111], v[62:63], v[176:177]
	v_add_f32_e32 v140, v98, v99
	v_add_f32_e32 v141, v100, v101
	v_add_f32_e32 v142, v174, v175
	v_add_f32_e32 v144, v176, v177
	v_pk_mul_f32 v[98:99], v[108:109], v[52:53]
	v_pk_mul_f32 v[100:101], v[108:109], v[60:61]
	v_pk_mul_f32 v[174:175], v[108:109], v[56:57]
	v_pk_mul_f32 v[176:177], v[108:109], v[64:65]
	v_pk_fma_f32 v[98:99], v[106:107], v[50:51], v[98:99]
	v_pk_fma_f32 v[100:101], v[106:107], v[58:59], v[100:101]
	v_pk_fma_f32 v[174:175], v[106:107], v[54:55], v[174:175]
	v_pk_fma_f32 v[176:177], v[106:107], v[62:63], v[176:177]
	v_add_f32_e32 v147, v98, v99
	v_add_f32_e32 v148, v100, v101
	v_add_f32_e32 v149, v174, v175
	v_add_f32_e32 v150, v176, v177
	v_pk_mul_f32 v[98:99], v[104:105], v[52:53]
	v_pk_mul_f32 v[100:101], v[104:105], v[60:61]
	v_pk_mul_f32 v[174:175], v[104:105], v[56:57]
	v_pk_mul_f32 v[176:177], v[104:105], v[64:65]
	v_pk_fma_f32 v[98:99], v[102:103], v[50:51], v[98:99]
	v_pk_fma_f32 v[100:101], v[102:103], v[58:59], v[100:101]
	v_pk_fma_f32 v[174:175], v[102:103], v[54:55], v[174:175]
	v_pk_fma_f32 v[176:177], v[102:103], v[62:63], v[176:177]
	v_add_f32_e32 v151, v98, v99
	v_add_f32_e32 v152, v100, v101
	v_add_f32_e32 v153, v174, v175
	v_add_f32_e32 v154, v176, v177
	v_add_f32_e32 v155, v146, v171
	v_add_f32_e32 v156, v155, v170
	v_add_f32_e32 v157, v156, v169
	v_add_f32_dpp v136, v136, v136 row_mirror row_mask:0xf bank_mask:0x3 bound_ctrl:1
	v_add_f32_dpp v137, v137, v137 row_mirror row_mask:0xf bank_mask:0x3 bound_ctrl:1
	v_add_f32_dpp v138, v138, v138 row_mirror row_mask:0xf bank_mask:0x3 bound_ctrl:1
	v_add_f32_dpp v139, v139, v139 row_mirror row_mask:0xf bank_mask:0x3 bound_ctrl:1
	v_add_f32_dpp v140, v140, v140 row_mirror row_mask:0xf bank_mask:0x3 bound_ctrl:1
	v_add_f32_dpp v141, v141, v141 row_mirror row_mask:0xf bank_mask:0x3 bound_ctrl:1
	v_add_f32_dpp v142, v142, v142 row_mirror row_mask:0xf bank_mask:0x3 bound_ctrl:1
	v_add_f32_dpp v144, v144, v144 row_mirror row_mask:0xf bank_mask:0x3 bound_ctrl:1
	v_add_f32_dpp v136, v147, v147 row_mirror row_mask:0xf bank_mask:0xc bound_ctrl:1
	v_add_f32_dpp v137, v148, v148 row_mirror row_mask:0xf bank_mask:0xc bound_ctrl:1
	v_add_f32_dpp v138, v149, v149 row_mirror row_mask:0xf bank_mask:0xc bound_ctrl:1
	v_add_f32_dpp v139, v150, v150 row_mirror row_mask:0xf bank_mask:0xc bound_ctrl:1
	v_add_f32_dpp v140, v151, v151 row_mirror row_mask:0xf bank_mask:0xc bound_ctrl:1
	v_add_f32_dpp v141, v152, v152 row_mirror row_mask:0xf bank_mask:0xc bound_ctrl:1
	v_add_f32_dpp v142, v153, v153 row_mirror row_mask:0xf bank_mask:0xc bound_ctrl:1
	v_add_f32_dpp v144, v154, v154 row_mirror row_mask:0xf bank_mask:0xc bound_ctrl:1
	v_add_f32_dpp v136, v136, v136 row_half_mirror row_mask:0xf bank_mask:0x5 bound_ctrl:1
	v_add_f32_dpp v137, v137, v137 row_half_mirror row_mask:0xf bank_mask:0x5 bound_ctrl:1
	v_add_f32_dpp v138, v138, v138 row_half_mirror row_mask:0xf bank_mask:0x5 bound_ctrl:1
	v_add_f32_dpp v139, v139, v139 row_half_mirror row_mask:0xf bank_mask:0x5 bound_ctrl:1
	v_add_f32_dpp v136, v140, v140 row_half_mirror row_mask:0xf bank_mask:0xa bound_ctrl:1
	v_add_f32_dpp v137, v141, v141 row_half_mirror row_mask:0xf bank_mask:0xa bound_ctrl:1
	v_add_f32_dpp v138, v142, v142 row_half_mirror row_mask:0xf bank_mask:0xa bound_ctrl:1
	v_add_f32_dpp v139, v144, v144 row_half_mirror row_mask:0xf bank_mask:0xa bound_ctrl:1
	v_add_f32_dpp v136, v136, v136 quad_perm:[2,3,0,1] row_mask:0xf bank_mask:0xf bound_ctrl:1
	v_add_f32_dpp v138, v138, v138 quad_perm:[2,3,0,1] row_mask:0xf bank_mask:0xf bound_ctrl:1
	v_add_f32_dpp v137, v137, v137 quad_perm:[2,3,0,1] row_mask:0xf bank_mask:0xf bound_ctrl:1
	v_add_f32_dpp v139, v139, v139 quad_perm:[2,3,0,1] row_mask:0xf bank_mask:0xf bound_ctrl:1
	v_cndmask_b32_e64 v173, v155, v146, s[28:29]
	v_cndmask_b32_e64 v178, v157, v156, s[28:29]
	v_cndmask_b32_e64 v136, v136, v138, s[24:25]
	v_cndmask_b32_e64 v137, v137, v139, s[24:25]
	v_cndmask_b32_e64 v173, v178, v173, s[24:25]
	v_add_f32_e32 v146, v157, v167
	v_add_f32_dpp v136, v136, v136 quad_perm:[1,0,3,2] row_mask:0xf bank_mask:0xf bound_ctrl:1
	v_add_f32_dpp v137, v137, v137 quad_perm:[1,0,3,2] row_mask:0xf bank_mask:0xf bound_ctrl:1
	v_cndmask_b32_e64 v136, v136, v137, s[28:29]
	v_fmac_f32_e32 v136, 0x3fb8aa3b, v173
	s_nop 1
	v_max_f32_dpp v179, v136, v136 quad_perm:[1,0,3,2] row_mask:0xf bank_mask:0xf bound_ctrl:1
	s_nop 1
	v_max_f32_dpp v180, v179, v179 quad_perm:[2,3,0,1] row_mask:0xf bank_mask:0xf bound_ctrl:1
	v_max_f32_e32 v180, v134, v180
	v_sub_f32_e32 v155, v134, v180
	v_sub_f32_e32 v156, v136, v180
	v_mov_b32_e32 v134, v180
	v_exp_f32_e32 v155, v155
	v_exp_f32_e32 v156, v156
	s_nop 0
	v_mov_b32_dpp v137, v155 row_newbcast:0 row_mask:0xf bank_mask:0xf
	v_mov_b32_dpp v142, v155 row_newbcast:4 row_mask:0xf bank_mask:0xf
	v_mov_b32_dpp v150, v155 row_newbcast:8 row_mask:0xf bank_mask:0xf
	v_mov_b32_dpp v178, v155 row_newbcast:12 row_mask:0xf bank_mask:0xf
	v_add_f32_dpp v157, v156, v156 quad_perm:[1,0,3,2] row_mask:0xf bank_mask:0xf bound_ctrl:1
	v_mov_b32_dpp v138, v156 row_newbcast:0 row_mask:0xf bank_mask:0xf
	v_mov_b32_dpp v139, v156 row_newbcast:1 row_mask:0xf bank_mask:0xf
	v_mov_b32_dpp v140, v156 row_newbcast:2 row_mask:0xf bank_mask:0xf
	v_mov_b32_dpp v141, v156 row_newbcast:3 row_mask:0xf bank_mask:0xf
	v_add_f32_dpp v173, v157, v157 quad_perm:[2,3,0,1] row_mask:0xf bank_mask:0xf bound_ctrl:1
	v_mov_b32_dpp v144, v156 row_newbcast:4 row_mask:0xf bank_mask:0xf
	v_mov_b32_dpp v147, v156 row_newbcast:5 row_mask:0xf bank_mask:0xf
	v_mov_b32_dpp v148, v156 row_newbcast:6 row_mask:0xf bank_mask:0xf
	v_mov_b32_dpp v149, v156 row_newbcast:7 row_mask:0xf bank_mask:0xf
	v_fma_f32 v135, v135, v155, v173
	v_mov_b32_dpp v151, v156 row_newbcast:8 row_mask:0xf bank_mask:0xf
	v_mov_b32_dpp v152, v156 row_newbcast:9 row_mask:0xf bank_mask:0xf
	v_mov_b32_dpp v153, v156 row_newbcast:10 row_mask:0xf bank_mask:0xf
	v_mov_b32_dpp v154, v156 row_newbcast:11 row_mask:0xf bank_mask:0xf
	v_mov_b32_dpp v179, v156 row_newbcast:12 row_mask:0xf bank_mask:0xf
	v_mov_b32_dpp v180, v156 row_newbcast:13 row_mask:0xf bank_mask:0xf
	v_mov_b32_dpp v181, v156 row_newbcast:14 row_mask:0xf bank_mask:0xf
	v_mov_b32_dpp v0, v156 row_newbcast:15 row_mask:0xf bank_mask:0xf
	v_pk_mul_f32 v[118:119], v[118:119], v[136:137] op_sel:[0,1] op_sel_hi:[1,1]
	v_pk_mul_f32 v[120:121], v[120:121], v[136:137] op_sel:[0,1] op_sel_hi:[1,1]
	v_pk_mul_f32 v[122:123], v[122:123], v[142:143] op_sel:[0,0] op_sel_hi:[1,0]
	v_pk_mul_f32 v[124:125], v[124:125], v[142:143] op_sel:[0,0] op_sel_hi:[1,0]
	v_pk_mul_f32 v[126:127], v[126:127], v[150:151] op_sel:[0,0] op_sel_hi:[1,0]
	v_pk_mul_f32 v[128:129], v[128:129], v[150:151] op_sel:[0,0] op_sel_hi:[1,0]
	v_pk_mul_f32 v[130:131], v[130:131], v[178:179] op_sel:[0,0] op_sel_hi:[1,0]
	v_pk_mul_f32 v[132:133], v[132:133], v[178:179] op_sel:[0,0] op_sel_hi:[1,0]
	v_pk_fma_f32 v[118:119], v[138:139], v[22:23], v[118:119] op_sel:[0,0,0] op_sel_hi:[0,1,1]
	v_pk_fma_f32 v[120:121], v[138:139], v[24:25], v[120:121] op_sel:[0,0,0] op_sel_hi:[0,1,1]
	v_pk_fma_f32 v[122:123], v[144:145], v[22:23], v[122:123] op_sel:[0,0,0] op_sel_hi:[0,1,1]
	v_pk_fma_f32 v[124:125], v[144:145], v[24:25], v[124:125] op_sel:[0,0,0] op_sel_hi:[0,1,1]
	v_pk_fma_f32 v[126:127], v[150:151], v[22:23], v[126:127] op_sel:[1,0,0] op_sel_hi:[1,1,1]
	v_pk_fma_f32 v[128:129], v[150:151], v[24:25], v[128:129] op_sel:[1,0,0] op_sel_hi:[1,1,1]
	v_pk_fma_f32 v[130:131], v[178:179], v[22:23], v[130:131] op_sel:[1,0,0] op_sel_hi:[1,1,1]
	v_pk_fma_f32 v[132:133], v[178:179], v[24:25], v[132:133] op_sel:[1,0,0] op_sel_hi:[1,1,1]
	v_pk_fma_f32 v[118:119], v[138:139], v[18:19], v[118:119] op_sel:[1,0,0] op_sel_hi:[1,1,1]
	v_pk_fma_f32 v[120:121], v[138:139], v[20:21], v[120:121] op_sel:[1,0,0] op_sel_hi:[1,1,1]
	v_pk_fma_f32 v[122:123], v[146:147], v[18:19], v[122:123] op_sel:[1,0,0] op_sel_hi:[1,1,1]
	v_pk_fma_f32 v[124:125], v[146:147], v[20:21], v[124:125] op_sel:[1,0,0] op_sel_hi:[1,1,1]
	v_pk_fma_f32 v[126:127], v[152:153], v[18:19], v[126:127] op_sel:[0,0,0] op_sel_hi:[0,1,1]
	v_pk_fma_f32 v[128:129], v[152:153], v[20:21], v[128:129] op_sel:[0,0,0] op_sel_hi:[0,1,1]
	v_pk_fma_f32 v[130:131], v[180:181], v[18:19], v[130:131] op_sel:[0,0,0] op_sel_hi:[0,1,1]
	v_pk_fma_f32 v[132:133], v[180:181], v[20:21], v[132:133] op_sel:[0,0,0] op_sel_hi:[0,1,1]
	v_pk_fma_f32 v[118:119], v[140:141], v[26:27], v[118:119] op_sel:[0,0,0] op_sel_hi:[0,1,1]
	v_pk_fma_f32 v[120:121], v[140:141], v[28:29], v[120:121] op_sel:[0,0,0] op_sel_hi:[0,1,1]
	v_pk_fma_f32 v[122:123], v[148:149], v[26:27], v[122:123] op_sel:[0,0,0] op_sel_hi:[0,1,1]
	v_pk_fma_f32 v[124:125], v[148:149], v[28:29], v[124:125] op_sel:[0,0,0] op_sel_hi:[0,1,1]
	v_pk_fma_f32 v[126:127], v[152:153], v[26:27], v[126:127] op_sel:[1,0,0] op_sel_hi:[1,1,1]
	v_pk_fma_f32 v[128:129], v[152:153], v[28:29], v[128:129] op_sel:[1,0,0] op_sel_hi:[1,1,1]
	v_pk_fma_f32 v[130:131], v[180:181], v[26:27], v[130:131] op_sel:[1,0,0] op_sel_hi:[1,1,1]
	v_pk_fma_f32 v[132:133], v[180:181], v[28:29], v[132:133] op_sel:[1,0,0] op_sel_hi:[1,1,1]
	v_pk_fma_f32 v[118:119], v[140:141], v[30:31], v[118:119] op_sel:[1,0,0] op_sel_hi:[1,1,1]
	v_pk_fma_f32 v[120:121], v[140:141], v[32:33], v[120:121] op_sel:[1,0,0] op_sel_hi:[1,1,1]
	v_pk_fma_f32 v[122:123], v[148:149], v[30:31], v[122:123] op_sel:[1,0,0] op_sel_hi:[1,1,1]
	v_pk_fma_f32 v[124:125], v[148:149], v[32:33], v[124:125] op_sel:[1,0,0] op_sel_hi:[1,1,1]
	v_pk_fma_f32 v[126:127], v[154:155], v[30:31], v[126:127] op_sel:[0,0,0] op_sel_hi:[0,1,1]
	v_pk_fma_f32 v[128:129], v[154:155], v[32:33], v[128:129] op_sel:[0,0,0] op_sel_hi:[0,1,1]
	v_pk_fma_f32 v[130:131], v[0:1], v[30:31], v[130:131] op_sel:[0,0,0] op_sel_hi:[0,1,1]
	v_pk_fma_f32 v[132:133], v[0:1], v[32:33], v[132:133] op_sel:[0,0,0] op_sel_hi:[0,1,1]
	s_waitcnt vmcnt(12)
	v_pk_mul_f32 v[98:99], v[116:117], v[36:37]
	v_pk_mul_f32 v[100:101], v[116:117], v[44:45]
	v_pk_mul_f32 v[174:175], v[116:117], v[40:41]
	v_pk_mul_f32 v[176:177], v[116:117], v[48:49]
	v_pk_fma_f32 v[98:99], v[114:115], v[34:35], v[98:99]
	v_pk_fma_f32 v[100:101], v[114:115], v[42:43], v[100:101]
	v_pk_fma_f32 v[174:175], v[114:115], v[38:39], v[174:175]
	v_pk_fma_f32 v[176:177], v[114:115], v[46:47], v[176:177]
	v_add_f32_e32 v136, v98, v99
	v_add_f32_e32 v137, v100, v101
	v_add_f32_e32 v138, v174, v175
	v_add_f32_e32 v139, v176, v177
	v_pk_mul_f32 v[98:99], v[112:113], v[36:37]
	v_pk_mul_f32 v[100:101], v[112:113], v[44:45]
	v_pk_mul_f32 v[174:175], v[112:113], v[40:41]
	v_pk_mul_f32 v[176:177], v[112:113], v[48:49]
	v_pk_fma_f32 v[98:99], v[110:111], v[34:35], v[98:99]
	v_pk_fma_f32 v[100:101], v[110:111], v[42:43], v[100:101]
	v_pk_fma_f32 v[174:175], v[110:111], v[38:39], v[174:175]
	v_pk_fma_f32 v[176:177], v[110:111], v[46:47], v[176:177]
	v_add_f32_e32 v140, v98, v99
	v_add_f32_e32 v141, v100, v101
	v_add_f32_e32 v142, v174, v175
	v_add_f32_e32 v144, v176, v177
	v_pk_mul_f32 v[98:99], v[108:109], v[36:37]
	v_pk_mul_f32 v[100:101], v[108:109], v[44:45]
	v_pk_mul_f32 v[174:175], v[108:109], v[40:41]
	v_pk_mul_f32 v[176:177], v[108:109], v[48:49]
	v_pk_fma_f32 v[98:99], v[106:107], v[34:35], v[98:99]
	v_pk_fma_f32 v[100:101], v[106:107], v[42:43], v[100:101]
	v_pk_fma_f32 v[174:175], v[106:107], v[38:39], v[174:175]
	v_pk_fma_f32 v[176:177], v[106:107], v[46:47], v[176:177]
	v_add_f32_e32 v147, v98, v99
	v_add_f32_e32 v148, v100, v101
	v_add_f32_e32 v149, v174, v175
	v_add_f32_e32 v150, v176, v177
	v_pk_mul_f32 v[98:99], v[104:105], v[36:37]
	v_pk_mul_f32 v[100:101], v[104:105], v[44:45]
	v_pk_mul_f32 v[174:175], v[104:105], v[40:41]
	v_pk_mul_f32 v[176:177], v[104:105], v[48:49]
	v_pk_fma_f32 v[98:99], v[102:103], v[34:35], v[98:99]
	v_pk_fma_f32 v[100:101], v[102:103], v[42:43], v[100:101]
	v_pk_fma_f32 v[174:175], v[102:103], v[38:39], v[174:175]
	v_pk_fma_f32 v[176:177], v[102:103], v[46:47], v[176:177]
	v_add_f32_e32 v151, v98, v99
	v_add_f32_e32 v152, v100, v101
	v_add_f32_e32 v153, v174, v175
	v_add_f32_e32 v154, v176, v177
	v_add_f32_e32 v155, v146, v166
	v_add_f32_e32 v156, v155, v165
	v_add_f32_e32 v157, v156, v164
	v_add_f32_dpp v136, v136, v136 row_mirror row_mask:0xf bank_mask:0x3 bound_ctrl:1
	v_add_f32_dpp v137, v137, v137 row_mirror row_mask:0xf bank_mask:0x3 bound_ctrl:1
	v_add_f32_dpp v138, v138, v138 row_mirror row_mask:0xf bank_mask:0x3 bound_ctrl:1
	v_add_f32_dpp v139, v139, v139 row_mirror row_mask:0xf bank_mask:0x3 bound_ctrl:1
	v_add_f32_dpp v140, v140, v140 row_mirror row_mask:0xf bank_mask:0x3 bound_ctrl:1
	v_add_f32_dpp v141, v141, v141 row_mirror row_mask:0xf bank_mask:0x3 bound_ctrl:1
	v_add_f32_dpp v142, v142, v142 row_mirror row_mask:0xf bank_mask:0x3 bound_ctrl:1
	v_add_f32_dpp v144, v144, v144 row_mirror row_mask:0xf bank_mask:0x3 bound_ctrl:1
	v_add_f32_dpp v136, v147, v147 row_mirror row_mask:0xf bank_mask:0xc bound_ctrl:1
	v_add_f32_dpp v137, v148, v148 row_mirror row_mask:0xf bank_mask:0xc bound_ctrl:1
	v_add_f32_dpp v138, v149, v149 row_mirror row_mask:0xf bank_mask:0xc bound_ctrl:1
	v_add_f32_dpp v139, v150, v150 row_mirror row_mask:0xf bank_mask:0xc bound_ctrl:1
	v_add_f32_dpp v140, v151, v151 row_mirror row_mask:0xf bank_mask:0xc bound_ctrl:1
	v_add_f32_dpp v141, v152, v152 row_mirror row_mask:0xf bank_mask:0xc bound_ctrl:1
	v_add_f32_dpp v142, v153, v153 row_mirror row_mask:0xf bank_mask:0xc bound_ctrl:1
	v_add_f32_dpp v144, v154, v154 row_mirror row_mask:0xf bank_mask:0xc bound_ctrl:1
	v_add_f32_dpp v136, v136, v136 row_half_mirror row_mask:0xf bank_mask:0x5 bound_ctrl:1
	v_add_f32_dpp v137, v137, v137 row_half_mirror row_mask:0xf bank_mask:0x5 bound_ctrl:1
	v_add_f32_dpp v138, v138, v138 row_half_mirror row_mask:0xf bank_mask:0x5 bound_ctrl:1
	v_add_f32_dpp v139, v139, v139 row_half_mirror row_mask:0xf bank_mask:0x5 bound_ctrl:1
	v_add_f32_dpp v136, v140, v140 row_half_mirror row_mask:0xf bank_mask:0xa bound_ctrl:1
	v_add_f32_dpp v137, v141, v141 row_half_mirror row_mask:0xf bank_mask:0xa bound_ctrl:1
	v_add_f32_dpp v138, v142, v142 row_half_mirror row_mask:0xf bank_mask:0xa bound_ctrl:1
	v_add_f32_dpp v139, v144, v144 row_half_mirror row_mask:0xf bank_mask:0xa bound_ctrl:1
	v_add_f32_dpp v136, v136, v136 quad_perm:[2,3,0,1] row_mask:0xf bank_mask:0xf bound_ctrl:1
	v_add_f32_dpp v138, v138, v138 quad_perm:[2,3,0,1] row_mask:0xf bank_mask:0xf bound_ctrl:1
	v_add_f32_dpp v137, v137, v137 quad_perm:[2,3,0,1] row_mask:0xf bank_mask:0xf bound_ctrl:1
	v_add_f32_dpp v139, v139, v139 quad_perm:[2,3,0,1] row_mask:0xf bank_mask:0xf bound_ctrl:1
	v_cndmask_b32_e64 v173, v155, v146, s[28:29]
	v_cndmask_b32_e64 v178, v157, v156, s[28:29]
	v_cndmask_b32_e64 v136, v136, v138, s[24:25]
	v_cndmask_b32_e64 v137, v137, v139, s[24:25]
	v_cndmask_b32_e64 v173, v178, v173, s[24:25]
	v_add_f32_e32 v146, v157, v168
	v_add_f32_dpp v136, v136, v136 quad_perm:[1,0,3,2] row_mask:0xf bank_mask:0xf bound_ctrl:1
	v_add_f32_dpp v137, v137, v137 quad_perm:[1,0,3,2] row_mask:0xf bank_mask:0xf bound_ctrl:1
	v_cndmask_b32_e64 v136, v136, v137, s[28:29]
	v_fmac_f32_e32 v136, 0x3fb8aa3b, v173
	s_nop 1
	v_max_f32_dpp v179, v136, v136 quad_perm:[1,0,3,2] row_mask:0xf bank_mask:0xf bound_ctrl:1
	s_nop 1
	v_max_f32_dpp v180, v179, v179 quad_perm:[2,3,0,1] row_mask:0xf bank_mask:0xf bound_ctrl:1
	v_max_f32_e32 v180, v134, v180
	v_sub_f32_e32 v155, v134, v180
	v_sub_f32_e32 v156, v136, v180
	v_mov_b32_e32 v134, v180
	v_exp_f32_e32 v155, v155
	v_exp_f32_e32 v156, v156
	s_nop 0
	v_mov_b32_dpp v137, v155 row_newbcast:0 row_mask:0xf bank_mask:0xf
	v_mov_b32_dpp v142, v155 row_newbcast:4 row_mask:0xf bank_mask:0xf
	v_mov_b32_dpp v150, v155 row_newbcast:8 row_mask:0xf bank_mask:0xf
	v_mov_b32_dpp v178, v155 row_newbcast:12 row_mask:0xf bank_mask:0xf
	v_add_f32_dpp v157, v156, v156 quad_perm:[1,0,3,2] row_mask:0xf bank_mask:0xf bound_ctrl:1
	v_mov_b32_dpp v138, v156 row_newbcast:0 row_mask:0xf bank_mask:0xf
	v_mov_b32_dpp v139, v156 row_newbcast:1 row_mask:0xf bank_mask:0xf
	v_mov_b32_dpp v140, v156 row_newbcast:2 row_mask:0xf bank_mask:0xf
	v_mov_b32_dpp v141, v156 row_newbcast:3 row_mask:0xf bank_mask:0xf
	v_add_f32_dpp v173, v157, v157 quad_perm:[2,3,0,1] row_mask:0xf bank_mask:0xf bound_ctrl:1
	v_mov_b32_dpp v144, v156 row_newbcast:4 row_mask:0xf bank_mask:0xf
	v_mov_b32_dpp v147, v156 row_newbcast:5 row_mask:0xf bank_mask:0xf
	v_mov_b32_dpp v148, v156 row_newbcast:6 row_mask:0xf bank_mask:0xf
	v_mov_b32_dpp v149, v156 row_newbcast:7 row_mask:0xf bank_mask:0xf
	v_fma_f32 v135, v135, v155, v173
	v_mov_b32_dpp v151, v156 row_newbcast:8 row_mask:0xf bank_mask:0xf
	v_mov_b32_dpp v152, v156 row_newbcast:9 row_mask:0xf bank_mask:0xf
	v_mov_b32_dpp v153, v156 row_newbcast:10 row_mask:0xf bank_mask:0xf
	v_mov_b32_dpp v154, v156 row_newbcast:11 row_mask:0xf bank_mask:0xf
	v_mov_b32_dpp v179, v156 row_newbcast:12 row_mask:0xf bank_mask:0xf
	v_mov_b32_dpp v180, v156 row_newbcast:13 row_mask:0xf bank_mask:0xf
	v_mov_b32_dpp v181, v156 row_newbcast:14 row_mask:0xf bank_mask:0xf
	v_mov_b32_dpp v0, v156 row_newbcast:15 row_mask:0xf bank_mask:0xf
	v_pk_mul_f32 v[118:119], v[118:119], v[136:137] op_sel:[0,1] op_sel_hi:[1,1]
	v_pk_mul_f32 v[120:121], v[120:121], v[136:137] op_sel:[0,1] op_sel_hi:[1,1]
	v_pk_mul_f32 v[122:123], v[122:123], v[142:143] op_sel:[0,0] op_sel_hi:[1,0]
	v_pk_mul_f32 v[124:125], v[124:125], v[142:143] op_sel:[0,0] op_sel_hi:[1,0]
	v_pk_mul_f32 v[126:127], v[126:127], v[150:151] op_sel:[0,0] op_sel_hi:[1,0]
	v_pk_mul_f32 v[128:129], v[128:129], v[150:151] op_sel:[0,0] op_sel_hi:[1,0]
	v_pk_mul_f32 v[130:131], v[130:131], v[178:179] op_sel:[0,0] op_sel_hi:[1,0]
	v_pk_mul_f32 v[132:133], v[132:133], v[178:179] op_sel:[0,0] op_sel_hi:[1,0]
	v_pk_fma_f32 v[118:119], v[138:139], v[2:3], v[118:119] op_sel:[0,0,0] op_sel_hi:[0,1,1]
	v_pk_fma_f32 v[120:121], v[138:139], v[4:5], v[120:121] op_sel:[0,0,0] op_sel_hi:[0,1,1]
	v_pk_fma_f32 v[122:123], v[144:145], v[2:3], v[122:123] op_sel:[0,0,0] op_sel_hi:[0,1,1]
	v_pk_fma_f32 v[124:125], v[144:145], v[4:5], v[124:125] op_sel:[0,0,0] op_sel_hi:[0,1,1]
	v_pk_fma_f32 v[126:127], v[150:151], v[2:3], v[126:127] op_sel:[1,0,0] op_sel_hi:[1,1,1]
	v_pk_fma_f32 v[128:129], v[150:151], v[4:5], v[128:129] op_sel:[1,0,0] op_sel_hi:[1,1,1]
	v_pk_fma_f32 v[130:131], v[178:179], v[2:3], v[130:131] op_sel:[1,0,0] op_sel_hi:[1,1,1]
	v_pk_fma_f32 v[132:133], v[178:179], v[4:5], v[132:133] op_sel:[1,0,0] op_sel_hi:[1,1,1]
	v_pk_fma_f32 v[118:119], v[138:139], v[6:7], v[118:119] op_sel:[1,0,0] op_sel_hi:[1,1,1]
	v_pk_fma_f32 v[120:121], v[138:139], v[8:9], v[120:121] op_sel:[1,0,0] op_sel_hi:[1,1,1]
	v_pk_fma_f32 v[122:123], v[146:147], v[6:7], v[122:123] op_sel:[1,0,0] op_sel_hi:[1,1,1]
	v_pk_fma_f32 v[124:125], v[146:147], v[8:9], v[124:125] op_sel:[1,0,0] op_sel_hi:[1,1,1]
	v_pk_fma_f32 v[126:127], v[152:153], v[6:7], v[126:127] op_sel:[0,0,0] op_sel_hi:[0,1,1]
	v_pk_fma_f32 v[128:129], v[152:153], v[8:9], v[128:129] op_sel:[0,0,0] op_sel_hi:[0,1,1]
	v_pk_fma_f32 v[130:131], v[180:181], v[6:7], v[130:131] op_sel:[0,0,0] op_sel_hi:[0,1,1]
	v_pk_fma_f32 v[132:133], v[180:181], v[8:9], v[132:133] op_sel:[0,0,0] op_sel_hi:[0,1,1]
	v_pk_fma_f32 v[118:119], v[140:141], v[10:11], v[118:119] op_sel:[0,0,0] op_sel_hi:[0,1,1]
	v_pk_fma_f32 v[120:121], v[140:141], v[12:13], v[120:121] op_sel:[0,0,0] op_sel_hi:[0,1,1]
	v_pk_fma_f32 v[122:123], v[148:149], v[10:11], v[122:123] op_sel:[0,0,0] op_sel_hi:[0,1,1]
	v_pk_fma_f32 v[124:125], v[148:149], v[12:13], v[124:125] op_sel:[0,0,0] op_sel_hi:[0,1,1]
	v_pk_fma_f32 v[126:127], v[152:153], v[10:11], v[126:127] op_sel:[1,0,0] op_sel_hi:[1,1,1]
	v_pk_fma_f32 v[128:129], v[152:153], v[12:13], v[128:129] op_sel:[1,0,0] op_sel_hi:[1,1,1]
	v_pk_fma_f32 v[130:131], v[180:181], v[10:11], v[130:131] op_sel:[1,0,0] op_sel_hi:[1,1,1]
	v_pk_fma_f32 v[132:133], v[180:181], v[12:13], v[132:133] op_sel:[1,0,0] op_sel_hi:[1,1,1]
	v_pk_fma_f32 v[118:119], v[140:141], v[14:15], v[118:119] op_sel:[1,0,0] op_sel_hi:[1,1,1]
	v_pk_fma_f32 v[120:121], v[140:141], v[16:17], v[120:121] op_sel:[1,0,0] op_sel_hi:[1,1,1]
	v_pk_fma_f32 v[122:123], v[148:149], v[14:15], v[122:123] op_sel:[1,0,0] op_sel_hi:[1,1,1]
	v_pk_fma_f32 v[124:125], v[148:149], v[16:17], v[124:125] op_sel:[1,0,0] op_sel_hi:[1,1,1]
	v_pk_fma_f32 v[126:127], v[154:155], v[14:15], v[126:127] op_sel:[0,0,0] op_sel_hi:[0,1,1]
	v_pk_fma_f32 v[128:129], v[154:155], v[16:17], v[128:129] op_sel:[0,0,0] op_sel_hi:[0,1,1]
	v_pk_fma_f32 v[130:131], v[0:1], v[14:15], v[130:131] op_sel:[0,0,0] op_sel_hi:[0,1,1]
	v_pk_fma_f32 v[132:133], v[0:1], v[16:17], v[132:133] op_sel:[0,0,0] op_sel_hi:[0,1,1]
	s_waitcnt vmcnt(0)
	s_load_dwordx2 s[0:1], s[42:43], 0x100
	v_lshl_add_u32 v155, s40, 2, v160
	v_lshlrev_b32_e32 v156, 10, v155
	v_lshl_add_u32 v156, v159, 4, v156
	v_lshlrev_b32_e32 v157, 5, v155
	v_lshrrev_b32_e32 v173, 2, v159
	v_lshl_add_u32 v157, v173, 3, v157
	v_and_b32_e32 v173, 3, v159
	v_cmp_eq_u32_e32 vcc, 0, v173
	s_waitcnt lgkmcnt(0)
	s_add_u32 s4, s0, 0x4780000
	s_addc_u32 s5, s1, 0
	s_add_u32 s6, s0, 0x4f80000
	s_addc_u32 s7, s1, 0
	global_store_dwordx4 v156, v[118:121], s[4:5]
	global_store_dwordx4 v156, v[122:125], s[4:5] offset:256
	global_store_dwordx4 v156, v[126:129], s[4:5] offset:512
	global_store_dwordx4 v156, v[130:133], s[4:5] offset:768
	s_and_saveexec_b64 s[2:3], vcc
	global_store_dwordx2 v157, v[134:135], s[6:7]
	s_branch .LBB0_321
